# adds: K-loop MFMA segments raise priority before the opening barrier and drop the already-satisfied lgkmcnt wait after it
# speedup vs baseline: 1.0035x; 1.0017x over previous
.Lmy_sk1:
	s_waitcnt lgkmcnt(0)
	s_setprio 1
	s_barrier
	v_mfma_f32_16x16x32_bf16 v[128:131], v[132:135], v[184:187], v[128:131]
	v_mfma_f32_16x16x32_bf16 v[124:127], v[140:143], v[184:187], v[124:127]
	v_mfma_f32_16x16x32_bf16 v[120:123], v[132:135], v[192:195], v[120:123]
	v_mfma_f32_16x16x32_bf16 v[112:115], v[140:143], v[192:195], v[112:115]
	v_mfma_f32_16x16x32_bf16 v[104:107], v[132:135], v[208:211], v[104:107]
	v_mfma_f32_16x16x32_bf16 v[94:97], v[140:143], v[208:211], v[94:97]
	v_mfma_f32_16x16x32_bf16 v[86:89], v[132:135], v[216:219], v[86:89]
	v_mfma_f32_16x16x32_bf16 v[78:81], v[140:143], v[216:219], v[78:81]
	v_mfma_f32_16x16x32_bf16 v[128:131], v[136:139], v[188:191], v[128:131]
	v_mfma_f32_16x16x32_bf16 v[124:127], v[144:147], v[188:191], v[124:127]
	v_mfma_f32_16x16x32_bf16 v[120:123], v[136:139], v[204:207], v[120:123]
	v_mfma_f32_16x16x32_bf16 v[112:115], v[144:147], v[204:207], v[112:115]
	v_mfma_f32_16x16x32_bf16 v[104:107], v[136:139], v[212:215], v[104:107]
	v_mfma_f32_16x16x32_bf16 v[94:97], v[144:147], v[212:215], v[94:97]
	v_mfma_f32_16x16x32_bf16 v[86:89], v[136:139], v[220:223], v[86:89]
	v_mfma_f32_16x16x32_bf16 v[78:81], v[144:147], v[220:223], v[78:81]
	s_setprio 0
	s_setprio 1
	v_mfma_f32_16x16x32_bf16 v[116:119], v[156:159], v[184:187], v[116:119]
	v_mfma_f32_16x16x32_bf16 v[108:111], v[164:167], v[184:187], v[108:111]
	v_mfma_f32_16x16x32_bf16 v[100:103], v[156:159], v[192:195], v[100:103]
	v_mfma_f32_16x16x32_bf16 v[90:93], v[164:167], v[192:195], v[90:93]
	v_mfma_f32_16x16x32_bf16 v[82:85], v[156:159], v[208:211], v[82:85]
	v_mfma_f32_16x16x32_bf16 v[74:77], v[164:167], v[208:211], v[74:77]
	v_mfma_f32_16x16x32_bf16 v[70:73], v[156:159], v[216:219], v[70:73]
	v_mfma_f32_16x16x32_bf16 v[66:69], v[164:167], v[216:219], v[66:69]
	v_mfma_f32_16x16x32_bf16 v[116:119], v[160:163], v[188:191], v[116:119]
	v_mfma_f32_16x16x32_bf16 v[108:111], v[180:183], v[188:191], v[108:111]
	v_mfma_f32_16x16x32_bf16 v[100:103], v[160:163], v[204:207], v[100:103]
	v_mfma_f32_16x16x32_bf16 v[90:93], v[180:183], v[204:207], v[90:93]
	v_mfma_f32_16x16x32_bf16 v[82:85], v[160:163], v[212:215], v[82:85]
	v_mfma_f32_16x16x32_bf16 v[74:77], v[180:183], v[212:215], v[74:77]
	v_mfma_f32_16x16x32_bf16 v[70:73], v[160:163], v[220:223], v[70:73]
	v_mfma_f32_16x16x32_bf16 v[66:69], v[180:183], v[220:223], v[66:69]
	s_setprio 0
	s_barrier
	s_add_i32 s5, s44, s77
	v_lshl_add_u64 v[168:169], s[68:69], 0, v[148:149]
	s_mov_b32 m0, s5
	ds_read_b128 v[184:187], v179 offset:16384
	ds_read_b128 v[188:191], v179 offset:17408
	ds_read_b128 v[192:195], v179 offset:18432
	ds_read_b128 v[204:207], v179 offset:19456
	ds_read_b128 v[208:211], v179 offset:20480
	ds_read_b128 v[212:215], v179 offset:21504
	ds_read_b128 v[216:219], v179 offset:22528
	ds_read_b128 v[220:223], v179 offset:23552
	global_load_lds_dwordx4 v[168:169], off
	s_add_i32 m0, s5, 0x2000
	s_add_u32 s44, s68, 0x40000
	v_lshl_add_u64 v[172:173], s[68:69], 0, v[152:153]
	s_addc_u32 s45, s69, 0
	s_add_i32 s4, s4, s77
	global_load_lds_dwordx4 v[172:173], off
	v_lshl_add_u64 v[176:177], s[44:45], 0, v[148:149]
	s_mov_b32 m0, s4
	v_lshl_add_u64 v[200:201], s[70:71], 0, v[150:151]
	global_load_lds_dwordx4 v[176:177], off
	v_lshl_add_u64 v[176:177], s[44:45], 0, v[152:153]
	s_add_i32 m0, s4, 0x2000
	s_nop 0
	global_load_lds_dwordx4 v[176:177], off
	v_lshl_add_u64 v[176:177], s[70:71], 0, v[98:99]
	s_mov_b32 m0, s94
	s_nop 0
	global_load_lds_dwordx4 v[176:177], off
	s_add_i32 m0, s94, 0x2000
	s_nop 0
	global_load_lds_dwordx4 v[200:201], off
	s_cmp_eq_u32 s100, 1
	s_cbranch_scc1 .Lmy_sk2
	s_waitcnt vmcnt(8)
.Lmy_sk2:
	s_waitcnt lgkmcnt(0)
	s_setprio 1
	s_barrier
	v_mfma_f32_16x16x32_bf16 v[62:65], v[132:135], v[184:187], v[62:65]
	v_mfma_f32_16x16x32_bf16 v[58:61], v[140:143], v[184:187], v[58:61]
	v_mfma_f32_16x16x32_bf16 v[54:57], v[132:135], v[192:195], v[54:57]
	v_mfma_f32_16x16x32_bf16 v[46:49], v[140:143], v[192:195], v[46:49]
	v_mfma_f32_16x16x32_bf16 v[38:41], v[132:135], v[208:211], v[38:41]
	v_mfma_f32_16x16x32_bf16 v[30:33], v[140:143], v[208:211], v[30:33]
	v_mfma_f32_16x16x32_bf16 v[22:25], v[132:135], v[216:219], v[22:25]
	v_mfma_f32_16x16x32_bf16 v[14:17], v[140:143], v[216:219], v[14:17]
	v_mfma_f32_16x16x32_bf16 v[62:65], v[136:139], v[188:191], v[62:65]
	v_mfma_f32_16x16x32_bf16 v[58:61], v[144:147], v[188:191], v[58:61]
	v_mfma_f32_16x16x32_bf16 v[54:57], v[136:139], v[204:207], v[54:57]
	v_mfma_f32_16x16x32_bf16 v[46:49], v[144:147], v[204:207], v[46:49]
	v_mfma_f32_16x16x32_bf16 v[38:41], v[136:139], v[212:215], v[38:41]
	v_mfma_f32_16x16x32_bf16 v[30:33], v[144:147], v[212:215], v[30:33]
	v_mfma_f32_16x16x32_bf16 v[22:25], v[136:139], v[220:223], v[22:25]
	v_mfma_f32_16x16x32_bf16 v[14:17], v[144:147], v[220:223], v[14:17]
	s_setprio 0
	s_setprio 1
	v_mfma_f32_16x16x32_bf16 v[50:53], v[156:159], v[184:187], v[50:53]
	v_mfma_f32_16x16x32_bf16 v[42:45], v[164:167], v[184:187], v[42:45]
	v_mfma_f32_16x16x32_bf16 v[34:37], v[156:159], v[192:195], v[34:37]
	v_mfma_f32_16x16x32_bf16 v[26:29], v[164:167], v[192:195], v[26:29]
	v_mfma_f32_16x16x32_bf16 v[18:21], v[156:159], v[208:211], v[18:21]
	v_mfma_f32_16x16x32_bf16 v[10:13], v[164:167], v[208:211], v[10:13]
	v_mfma_f32_16x16x32_bf16 v[6:9], v[156:159], v[216:219], v[6:9]
	v_mfma_f32_16x16x32_bf16 v[2:5], v[164:167], v[216:219], v[2:5]
	v_mfma_f32_16x16x32_bf16 v[50:53], v[160:163], v[188:191], v[50:53]
	v_mfma_f32_16x16x32_bf16 v[42:45], v[180:183], v[188:191], v[42:45]
	v_mfma_f32_16x16x32_bf16 v[34:37], v[160:163], v[204:207], v[34:37]
	v_mfma_f32_16x16x32_bf16 v[26:29], v[180:183], v[204:207], v[26:29]
	v_mfma_f32_16x16x32_bf16 v[18:21], v[160:163], v[212:215], v[18:21]
	v_mfma_f32_16x16x32_bf16 v[10:13], v[180:183], v[212:215], v[10:13]
	v_mfma_f32_16x16x32_bf16 v[6:9], v[160:163], v[220:223], v[6:9]
	v_mfma_f32_16x16x32_bf16 v[2:5], v[180:183], v[220:223], v[2:5]
	s_setprio 0
	s_barrier
	s_add_i32 s4, 0, 0x18000
	s_add_i32 s5, 0, 0x1c000
	v_add_u32_e32 v144, s4, v175
	v_add_u32_e32 v170, s5, v175
	ds_read_b128 v[132:135], v144
	ds_read_b128 v[136:139], v144 offset:1024
	ds_read_b128 v[140:143], v144 offset:2048
	ds_read_b128 v[144:147], v144 offset:3072
	ds_read_b128 v[156:159], v170
	ds_read_b128 v[160:163], v170 offset:1024
	ds_read_b128 v[164:167], v170 offset:2048
	ds_read_b128 v[180:183], v170 offset:3072
	s_add_u32 s44, s70, 0x40000
	s_addc_u32 s45, s71, 0
	v_lshl_add_u64 v[202:203], s[44:45], 0, v[98:99]
	s_add_i32 m0, s94, 0x4000
	ds_read_b128 v[184:187], v179 offset:32768
	ds_read_b128 v[188:191], v179 offset:33792
	ds_read_b128 v[192:195], v179 offset:34816
	ds_read_b128 v[204:207], v179 offset:35840
	ds_read_b128 v[208:211], v179 offset:36864
	ds_read_b128 v[212:215], v179 offset:37888
	ds_read_b128 v[216:219], v179 offset:38912
	ds_read_b128 v[220:223], v179 offset:39936
	global_load_lds_dwordx4 v[202:203], off
	v_lshl_add_u64 v[202:203], s[44:45], 0, v[150:151]
	s_add_i32 m0, s94, 0x6000
	s_nop 0
	global_load_lds_dwordx4 v[202:203], off
	s_waitcnt vmcnt(8)
	s_waitcnt lgkmcnt(0)
	s_setprio 1
	s_barrier
	v_mfma_f32_16x16x32_bf16 v[128:131], v[132:135], v[184:187], v[128:131]
	v_mfma_f32_16x16x32_bf16 v[124:127], v[140:143], v[184:187], v[124:127]
	v_mfma_f32_16x16x32_bf16 v[120:123], v[132:135], v[192:195], v[120:123]
	v_mfma_f32_16x16x32_bf16 v[112:115], v[140:143], v[192:195], v[112:115]
	v_mfma_f32_16x16x32_bf16 v[104:107], v[132:135], v[208:211], v[104:107]
	v_mfma_f32_16x16x32_bf16 v[94:97], v[140:143], v[208:211], v[94:97]
	v_mfma_f32_16x16x32_bf16 v[86:89], v[132:135], v[216:219], v[86:89]
	v_mfma_f32_16x16x32_bf16 v[78:81], v[140:143], v[216:219], v[78:81]
	v_mfma_f32_16x16x32_bf16 v[128:131], v[136:139], v[188:191], v[128:131]
	v_mfma_f32_16x16x32_bf16 v[124:127], v[144:147], v[188:191], v[124:127]
	v_mfma_f32_16x16x32_bf16 v[120:123], v[136:139], v[204:207], v[120:123]
	v_mfma_f32_16x16x32_bf16 v[112:115], v[144:147], v[204:207], v[112:115]
	v_mfma_f32_16x16x32_bf16 v[104:107], v[136:139], v[212:215], v[104:107]
	v_mfma_f32_16x16x32_bf16 v[94:97], v[144:147], v[212:215], v[94:97]
	v_mfma_f32_16x16x32_bf16 v[86:89], v[136:139], v[220:223], v[86:89]
	v_mfma_f32_16x16x32_bf16 v[78:81], v[144:147], v[220:223], v[78:81]
	s_setprio 0
	s_setprio 1
	v_mfma_f32_16x16x32_bf16 v[116:119], v[156:159], v[184:187], v[116:119]
	v_mfma_f32_16x16x32_bf16 v[108:111], v[164:167], v[184:187], v[108:111]
	v_mfma_f32_16x16x32_bf16 v[100:103], v[156:159], v[192:195], v[100:103]
	v_mfma_f32_16x16x32_bf16 v[90:93], v[164:167], v[192:195], v[90:93]
	v_mfma_f32_16x16x32_bf16 v[82:85], v[156:159], v[208:211], v[82:85]
	v_mfma_f32_16x16x32_bf16 v[74:77], v[164:167], v[208:211], v[74:77]
	v_mfma_f32_16x16x32_bf16 v[70:73], v[156:159], v[216:219], v[70:73]
	v_mfma_f32_16x16x32_bf16 v[66:69], v[164:167], v[216:219], v[66:69]
	v_mfma_f32_16x16x32_bf16 v[116:119], v[160:163], v[188:191], v[116:119]
	v_mfma_f32_16x16x32_bf16 v[108:111], v[180:183], v[188:191], v[108:111]
	v_mfma_f32_16x16x32_bf16 v[100:103], v[160:163], v[204:207], v[100:103]
	v_mfma_f32_16x16x32_bf16 v[90:93], v[180:183], v[204:207], v[90:93]
	v_mfma_f32_16x16x32_bf16 v[82:85], v[160:163], v[212:215], v[82:85]
	v_mfma_f32_16x16x32_bf16 v[74:77], v[180:183], v[212:215], v[74:77]
	v_mfma_f32_16x16x32_bf16 v[70:73], v[160:163], v[220:223], v[70:73]
	v_mfma_f32_16x16x32_bf16 v[66:69], v[180:183], v[220:223], v[66:69]
	s_setprio 0
	s_barrier
	s_add_i32 s4, s4, s77
	v_lshl_add_u64 v[168:169], v[168:169], 0, s[42:43]
	s_mov_b32 m0, s4
	ds_read_b128 v[184:187], v179 offset:49152
	ds_read_b128 v[188:191], v179 offset:50176
	ds_read_b128 v[192:195], v179 offset:51200
	ds_read_b128 v[204:207], v179 offset:52224
	ds_read_b128 v[208:211], v179 offset:53248
	ds_read_b128 v[212:215], v179 offset:54272
	ds_read_b128 v[216:219], v179 offset:55296
	ds_read_b128 v[220:223], v179 offset:56320
	global_load_lds_dwordx4 v[168:169], off
	s_add_i32 m0, s4, 0x2000
	s_add_u32 s44, s68, 0x40080
	v_lshl_add_u64 v[168:169], v[172:173], 0, s[42:43]
	s_addc_u32 s45, s69, 0
	s_add_i32 s4, s5, s77
	global_load_lds_dwordx4 v[168:169], off
	v_lshl_add_u64 v[168:169], s[44:45], 0, v[148:149]
	s_mov_b32 m0, s4
	s_nop 0
	global_load_lds_dwordx4 v[168:169], off
	v_lshl_add_u64 v[168:169], s[44:45], 0, v[152:153]
	s_add_i32 m0, s4, 0x2000
	s_nop 0
	global_load_lds_dwordx4 v[168:169], off
	v_lshl_add_u64 v[168:169], v[176:177], 0, s[42:43]
	s_add_i32 m0, s94, 0x8000
	s_nop 0
	global_load_lds_dwordx4 v[168:169], off
	v_lshl_add_u64 v[168:169], v[200:201], 0, s[42:43]
	s_add_i32 m0, s94, 0xa000
	s_nop 0
	global_load_lds_dwordx4 v[168:169], off
	s_waitcnt vmcnt(8)
	s_waitcnt lgkmcnt(0)
	s_setprio 1
	s_barrier
	v_mfma_f32_16x16x32_bf16 v[62:65], v[132:135], v[184:187], v[62:65]
	v_mfma_f32_16x16x32_bf16 v[58:61], v[140:143], v[184:187], v[58:61]
	v_mfma_f32_16x16x32_bf16 v[54:57], v[132:135], v[192:195], v[54:57]
	v_mfma_f32_16x16x32_bf16 v[46:49], v[140:143], v[192:195], v[46:49]
	v_mfma_f32_16x16x32_bf16 v[38:41], v[132:135], v[208:211], v[38:41]
	v_mfma_f32_16x16x32_bf16 v[30:33], v[140:143], v[208:211], v[30:33]
	v_mfma_f32_16x16x32_bf16 v[22:25], v[132:135], v[216:219], v[22:25]
	v_mfma_f32_16x16x32_bf16 v[14:17], v[140:143], v[216:219], v[14:17]
	v_mfma_f32_16x16x32_bf16 v[62:65], v[136:139], v[188:191], v[62:65]
	v_mfma_f32_16x16x32_bf16 v[58:61], v[144:147], v[188:191], v[58:61]
	v_mfma_f32_16x16x32_bf16 v[54:57], v[136:139], v[204:207], v[54:57]
	v_mfma_f32_16x16x32_bf16 v[46:49], v[144:147], v[204:207], v[46:49]
	v_mfma_f32_16x16x32_bf16 v[38:41], v[136:139], v[212:215], v[38:41]
	v_mfma_f32_16x16x32_bf16 v[30:33], v[144:147], v[212:215], v[30:33]
	v_mfma_f32_16x16x32_bf16 v[22:25], v[136:139], v[220:223], v[22:25]
	v_mfma_f32_16x16x32_bf16 v[14:17], v[144:147], v[220:223], v[14:17]
	s_setprio 0
	s_setprio 1
	v_mfma_f32_16x16x32_bf16 v[50:53], v[156:159], v[184:187], v[50:53]
	v_mfma_f32_16x16x32_bf16 v[42:45], v[164:167], v[184:187], v[42:45]
	v_mfma_f32_16x16x32_bf16 v[34:37], v[156:159], v[192:195], v[34:37]
	v_mfma_f32_16x16x32_bf16 v[26:29], v[164:167], v[192:195], v[26:29]
	v_mfma_f32_16x16x32_bf16 v[18:21], v[156:159], v[208:211], v[18:21]
	v_mfma_f32_16x16x32_bf16 v[10:13], v[164:167], v[208:211], v[10:13]
	v_mfma_f32_16x16x32_bf16 v[6:9], v[156:159], v[216:219], v[6:9]
	v_mfma_f32_16x16x32_bf16 v[2:5], v[164:167], v[216:219], v[2:5]
	v_mfma_f32_16x16x32_bf16 v[50:53], v[160:163], v[188:191], v[50:53]
	v_mfma_f32_16x16x32_bf16 v[42:45], v[180:183], v[188:191], v[42:45]
	v_mfma_f32_16x16x32_bf16 v[34:37], v[160:163], v[204:207], v[34:37]
	v_mfma_f32_16x16x32_bf16 v[26:29], v[180:183], v[204:207], v[26:29]
	v_mfma_f32_16x16x32_bf16 v[18:21], v[160:163], v[212:215], v[18:21]
	v_mfma_f32_16x16x32_bf16 v[10:13], v[180:183], v[212:215], v[10:13]
	v_mfma_f32_16x16x32_bf16 v[6:9], v[160:163], v[220:223], v[6:9]
	v_mfma_f32_16x16x32_bf16 v[2:5], v[180:183], v[220:223], v[2:5]
	s_setprio 0
	s_barrier
	s_mov_b32 s100, 0
	s_add_i32 s93, s93, 2
	s_add_u32 s0, s0, 0x100
	s_addc_u32 s1, s1, 0
	s_add_u32 s91, s91, 0x100
	s_addc_u32 s92, s92, 0
	s_cmp_gt_u32 s93, 13
	s_cbranch_scc0 .LBB0_322
	s_mov_b32 s100, 1
	s_and_b64 vcc, exec, s[14:15]
	s_cbranch_vccz .LBB0_325
	s_barrier

.Lmy_sk3:
	s_waitcnt lgkmcnt(0)
	s_setprio 1
	s_barrier
	v_mfma_f32_16x16x32_bf16 v[160:163], v[90:93], v[164:167], v[160:163]
	v_mfma_f32_16x16x32_bf16 v[156:159], v[100:103], v[164:167], v[156:159]
	v_mfma_f32_16x16x32_bf16 v[144:147], v[90:93], v[172:175], v[144:147]
	v_mfma_f32_16x16x32_bf16 v[140:143], v[100:103], v[172:175], v[140:143]
	v_mfma_f32_16x16x32_bf16 v[124:127], v[90:93], v[180:183], v[124:127]
	v_mfma_f32_16x16x32_bf16 v[116:119], v[100:103], v[180:183], v[116:119]
	v_mfma_f32_16x16x32_bf16 v[78:81], v[90:93], v[188:191], v[78:81]
	v_mfma_f32_16x16x32_bf16 v[74:77], v[100:103], v[188:191], v[74:77]
	v_mfma_f32_16x16x32_bf16 v[160:163], v[94:97], v[168:171], v[160:163]
	v_mfma_f32_16x16x32_bf16 v[156:159], v[104:107], v[168:171], v[156:159]
	v_mfma_f32_16x16x32_bf16 v[144:147], v[94:97], v[176:179], v[144:147]
	v_mfma_f32_16x16x32_bf16 v[140:143], v[104:107], v[176:179], v[140:143]
	v_mfma_f32_16x16x32_bf16 v[124:127], v[94:97], v[184:187], v[124:127]
	v_mfma_f32_16x16x32_bf16 v[116:119], v[104:107], v[184:187], v[116:119]
	v_mfma_f32_16x16x32_bf16 v[78:81], v[94:97], v[192:195], v[78:81]
	v_mfma_f32_16x16x32_bf16 v[74:77], v[104:107], v[192:195], v[74:77]
	s_setprio 0
	s_setprio 1
	v_mfma_f32_16x16x32_bf16 v[152:155], v[108:111], v[164:167], v[152:155]
	v_mfma_f32_16x16x32_bf16 v[148:151], v[120:123], v[164:167], v[148:151]
	v_mfma_f32_16x16x32_bf16 v[136:139], v[108:111], v[172:175], v[136:139]
	v_mfma_f32_16x16x32_bf16 v[132:135], v[120:123], v[172:175], v[132:135]
	v_mfma_f32_16x16x32_bf16 v[86:89], v[108:111], v[180:183], v[86:89]
	v_mfma_f32_16x16x32_bf16 v[82:85], v[120:123], v[180:183], v[82:85]
	v_mfma_f32_16x16x32_bf16 v[70:73], v[108:111], v[188:191], v[70:73]
	v_mfma_f32_16x16x32_bf16 v[66:69], v[120:123], v[188:191], v[66:69]
	v_mfma_f32_16x16x32_bf16 v[152:155], v[112:115], v[168:171], v[152:155]
	v_mfma_f32_16x16x32_bf16 v[148:151], v[128:131], v[168:171], v[148:151]
	v_mfma_f32_16x16x32_bf16 v[136:139], v[112:115], v[176:179], v[136:139]
	v_mfma_f32_16x16x32_bf16 v[132:135], v[128:131], v[176:179], v[132:135]
	v_mfma_f32_16x16x32_bf16 v[86:89], v[112:115], v[184:187], v[86:89]
	v_mfma_f32_16x16x32_bf16 v[82:85], v[128:131], v[184:187], v[82:85]
	v_mfma_f32_16x16x32_bf16 v[70:73], v[112:115], v[192:195], v[70:73]
	v_mfma_f32_16x16x32_bf16 v[66:69], v[128:131], v[192:195], v[66:69]
	s_setprio 0
	s_barrier
	s_add_i32 s4, s45, s91
	v_lshl_add_u64 v[200:201], s[70:71], 0, v[204:205]
	s_mov_b32 m0, s4
	ds_read_b128 v[164:167], v241 offset:16384
	ds_read_b128 v[168:171], v241 offset:17408
	ds_read_b128 v[172:175], v241 offset:18432
	ds_read_b128 v[176:179], v241 offset:19456
	ds_read_b128 v[180:183], v241 offset:20480
	ds_read_b128 v[184:187], v241 offset:21504
	ds_read_b128 v[188:191], v241 offset:22528
	ds_read_b128 v[192:195], v241 offset:23552
	global_load_lds_dwordx4 v[200:201], off
	s_add_i32 m0, s4, 0x2000
	s_add_u32 s4, s70, 0x40000
	v_lshl_add_u64 v[202:203], s[70:71], 0, v[208:209]
	s_addc_u32 s5, s71, 0
	s_add_i32 s6, s6, s91
	global_load_lds_dwordx4 v[202:203], off
	v_lshl_add_u64 v[210:211], s[4:5], 0, v[204:205]
	s_mov_b32 m0, s6
	v_lshl_add_u64 v[212:213], s[74:75], 0, v[206:207]
	global_load_lds_dwordx4 v[210:211], off
	v_lshl_add_u64 v[210:211], s[4:5], 0, v[208:209]
	s_add_i32 m0, s6, 0x2000
	s_nop 0
	global_load_lds_dwordx4 v[210:211], off
	v_lshl_add_u64 v[210:211], s[74:75], 0, v[98:99]
	s_mov_b32 m0, s44
	s_nop 0
	global_load_lds_dwordx4 v[210:211], off
	s_add_i32 m0, s44, 0x2000
	s_nop 0
	global_load_lds_dwordx4 v[212:213], off
	s_cmp_eq_u32 s100, 1
	s_cbranch_scc1 .Lmy_sk4
	s_waitcnt vmcnt(8)
.Lmy_sk4:
	s_waitcnt lgkmcnt(0)
	s_setprio 1
	s_barrier
	v_mfma_f32_16x16x32_bf16 v[62:65], v[90:93], v[164:167], v[62:65]
	v_mfma_f32_16x16x32_bf16 v[58:61], v[100:103], v[164:167], v[58:61]
	v_mfma_f32_16x16x32_bf16 v[46:49], v[90:93], v[172:175], v[46:49]
	v_mfma_f32_16x16x32_bf16 v[42:45], v[100:103], v[172:175], v[42:45]
	v_mfma_f32_16x16x32_bf16 v[30:33], v[90:93], v[180:183], v[30:33]
	v_mfma_f32_16x16x32_bf16 v[26:29], v[100:103], v[180:183], v[26:29]
	v_mfma_f32_16x16x32_bf16 v[14:17], v[90:93], v[188:191], v[14:17]
	v_mfma_f32_16x16x32_bf16 v[10:13], v[100:103], v[188:191], v[10:13]
	v_mfma_f32_16x16x32_bf16 v[62:65], v[94:97], v[168:171], v[62:65]
	v_mfma_f32_16x16x32_bf16 v[58:61], v[104:107], v[168:171], v[58:61]
	v_mfma_f32_16x16x32_bf16 v[46:49], v[94:97], v[176:179], v[46:49]
	v_mfma_f32_16x16x32_bf16 v[42:45], v[104:107], v[176:179], v[42:45]
	v_mfma_f32_16x16x32_bf16 v[30:33], v[94:97], v[184:187], v[30:33]
	v_mfma_f32_16x16x32_bf16 v[26:29], v[104:107], v[184:187], v[26:29]
	v_mfma_f32_16x16x32_bf16 v[14:17], v[94:97], v[192:195], v[14:17]
	v_mfma_f32_16x16x32_bf16 v[10:13], v[104:107], v[192:195], v[10:13]
	s_setprio 0
	s_setprio 1
	v_mfma_f32_16x16x32_bf16 v[54:57], v[108:111], v[164:167], v[54:57]
	v_mfma_f32_16x16x32_bf16 v[50:53], v[120:123], v[164:167], v[50:53]
	v_mfma_f32_16x16x32_bf16 v[38:41], v[108:111], v[172:175], v[38:41]
	v_mfma_f32_16x16x32_bf16 v[34:37], v[120:123], v[172:175], v[34:37]
	v_mfma_f32_16x16x32_bf16 v[22:25], v[108:111], v[180:183], v[22:25]
	v_mfma_f32_16x16x32_bf16 v[18:21], v[120:123], v[180:183], v[18:21]
	v_mfma_f32_16x16x32_bf16 v[6:9], v[108:111], v[188:191], v[6:9]
	v_mfma_f32_16x16x32_bf16 v[2:5], v[120:123], v[188:191], v[2:5]
	v_mfma_f32_16x16x32_bf16 v[54:57], v[112:115], v[168:171], v[54:57]
	v_mfma_f32_16x16x32_bf16 v[50:53], v[128:131], v[168:171], v[50:53]
	v_mfma_f32_16x16x32_bf16 v[38:41], v[112:115], v[176:179], v[38:41]
	v_mfma_f32_16x16x32_bf16 v[34:37], v[128:131], v[176:179], v[34:37]
	v_mfma_f32_16x16x32_bf16 v[22:25], v[112:115], v[184:187], v[22:25]
	v_mfma_f32_16x16x32_bf16 v[18:21], v[128:131], v[184:187], v[18:21]
	v_mfma_f32_16x16x32_bf16 v[6:9], v[112:115], v[192:195], v[6:9]
	v_mfma_f32_16x16x32_bf16 v[2:5], v[128:131], v[192:195], v[2:5]
	s_setprio 0
	s_barrier
	s_add_i32 s6, 0, 0x18000
	s_add_i32 s7, 0, 0x1c000
	v_add_u32_e32 v104, s6, v239
	v_add_u32_e32 v128, s7, v239
	ds_read_b128 v[90:93], v104
	ds_read_b128 v[94:97], v104 offset:1024
	ds_read_b128 v[100:103], v104 offset:2048
	ds_read_b128 v[104:107], v104 offset:3072
	ds_read_b128 v[108:111], v128
	ds_read_b128 v[112:115], v128 offset:1024
	ds_read_b128 v[120:123], v128 offset:2048
	ds_read_b128 v[128:131], v128 offset:3072
	s_add_u32 s4, s74, 0x40000
	s_addc_u32 s5, s75, 0
	v_lshl_add_u64 v[214:215], s[4:5], 0, v[98:99]
	s_add_i32 m0, s44, 0x4000
	ds_read_b128 v[164:167], v241 offset:32768
	ds_read_b128 v[168:171], v241 offset:33792
	ds_read_b128 v[172:175], v241 offset:34816
	ds_read_b128 v[176:179], v241 offset:35840
	ds_read_b128 v[180:183], v241 offset:36864
	ds_read_b128 v[184:187], v241 offset:37888
	ds_read_b128 v[188:191], v241 offset:38912
	ds_read_b128 v[192:195], v241 offset:39936
	global_load_lds_dwordx4 v[214:215], off
	v_lshl_add_u64 v[214:215], s[4:5], 0, v[206:207]
	s_add_i32 m0, s44, 0x6000
	s_nop 0
	global_load_lds_dwordx4 v[214:215], off
	s_waitcnt vmcnt(8)
	s_waitcnt lgkmcnt(0)
	s_setprio 1
	s_barrier
	v_mfma_f32_16x16x32_bf16 v[160:163], v[90:93], v[164:167], v[160:163]
	v_mfma_f32_16x16x32_bf16 v[156:159], v[100:103], v[164:167], v[156:159]
	v_mfma_f32_16x16x32_bf16 v[144:147], v[90:93], v[172:175], v[144:147]
	v_mfma_f32_16x16x32_bf16 v[140:143], v[100:103], v[172:175], v[140:143]
	v_mfma_f32_16x16x32_bf16 v[124:127], v[90:93], v[180:183], v[124:127]
	v_mfma_f32_16x16x32_bf16 v[116:119], v[100:103], v[180:183], v[116:119]
	v_mfma_f32_16x16x32_bf16 v[78:81], v[90:93], v[188:191], v[78:81]
	v_mfma_f32_16x16x32_bf16 v[74:77], v[100:103], v[188:191], v[74:77]
	v_mfma_f32_16x16x32_bf16 v[160:163], v[94:97], v[168:171], v[160:163]
	v_mfma_f32_16x16x32_bf16 v[156:159], v[104:107], v[168:171], v[156:159]
	v_mfma_f32_16x16x32_bf16 v[144:147], v[94:97], v[176:179], v[144:147]
	v_mfma_f32_16x16x32_bf16 v[140:143], v[104:107], v[176:179], v[140:143]
	v_mfma_f32_16x16x32_bf16 v[124:127], v[94:97], v[184:187], v[124:127]
	v_mfma_f32_16x16x32_bf16 v[116:119], v[104:107], v[184:187], v[116:119]
	v_mfma_f32_16x16x32_bf16 v[78:81], v[94:97], v[192:195], v[78:81]
	v_mfma_f32_16x16x32_bf16 v[74:77], v[104:107], v[192:195], v[74:77]
	s_setprio 0
	s_setprio 1
	v_mfma_f32_16x16x32_bf16 v[152:155], v[108:111], v[164:167], v[152:155]
	v_mfma_f32_16x16x32_bf16 v[148:151], v[120:123], v[164:167], v[148:151]
	v_mfma_f32_16x16x32_bf16 v[136:139], v[108:111], v[172:175], v[136:139]
	v_mfma_f32_16x16x32_bf16 v[132:135], v[120:123], v[172:175], v[132:135]
	v_mfma_f32_16x16x32_bf16 v[86:89], v[108:111], v[180:183], v[86:89]
	v_mfma_f32_16x16x32_bf16 v[82:85], v[120:123], v[180:183], v[82:85]
	v_mfma_f32_16x16x32_bf16 v[70:73], v[108:111], v[188:191], v[70:73]
	v_mfma_f32_16x16x32_bf16 v[66:69], v[120:123], v[188:191], v[66:69]
	v_mfma_f32_16x16x32_bf16 v[152:155], v[112:115], v[168:171], v[152:155]
	v_mfma_f32_16x16x32_bf16 v[148:151], v[128:131], v[168:171], v[148:151]
	v_mfma_f32_16x16x32_bf16 v[136:139], v[112:115], v[176:179], v[136:139]
	v_mfma_f32_16x16x32_bf16 v[132:135], v[128:131], v[176:179], v[132:135]
	v_mfma_f32_16x16x32_bf16 v[86:89], v[112:115], v[184:187], v[86:89]
	v_mfma_f32_16x16x32_bf16 v[82:85], v[128:131], v[184:187], v[82:85]
	v_mfma_f32_16x16x32_bf16 v[70:73], v[112:115], v[192:195], v[70:73]
	v_mfma_f32_16x16x32_bf16 v[66:69], v[128:131], v[192:195], v[66:69]
	s_setprio 0
	s_barrier
	s_add_i32 s4, s6, s91
	v_lshl_add_u64 v[200:201], v[200:201], 0, s[42:43]
	s_mov_b32 m0, s4
	ds_read_b128 v[164:167], v241 offset:49152
	ds_read_b128 v[168:171], v241 offset:50176
	ds_read_b128 v[172:175], v241 offset:51200
	ds_read_b128 v[176:179], v241 offset:52224
	ds_read_b128 v[180:183], v241 offset:53248
	ds_read_b128 v[184:187], v241 offset:54272
	ds_read_b128 v[188:191], v241 offset:55296
	ds_read_b128 v[192:195], v241 offset:56320
	global_load_lds_dwordx4 v[200:201], off
	s_add_i32 m0, s4, 0x2000
	s_add_u32 s4, s70, 0x40080
	v_lshl_add_u64 v[200:201], v[202:203], 0, s[42:43]
	s_addc_u32 s5, s71, 0
	s_add_i32 s6, s7, s91
	global_load_lds_dwordx4 v[200:201], off
	v_lshl_add_u64 v[200:201], s[4:5], 0, v[204:205]
	s_mov_b32 m0, s6
	s_nop 0
	global_load_lds_dwordx4 v[200:201], off
	v_lshl_add_u64 v[200:201], s[4:5], 0, v[208:209]
	s_add_i32 m0, s6, 0x2000
	s_nop 0
	global_load_lds_dwordx4 v[200:201], off
	v_lshl_add_u64 v[200:201], v[210:211], 0, s[42:43]
	s_add_i32 m0, s44, 0x8000
	s_nop 0
	global_load_lds_dwordx4 v[200:201], off
	v_lshl_add_u64 v[200:201], v[212:213], 0, s[42:43]
	s_add_i32 m0, s44, 0xa000
	s_nop 0
	global_load_lds_dwordx4 v[200:201], off
	s_waitcnt vmcnt(8)
	s_waitcnt lgkmcnt(0)
	s_setprio 1
	s_barrier
	v_mfma_f32_16x16x32_bf16 v[62:65], v[90:93], v[164:167], v[62:65]
	v_mfma_f32_16x16x32_bf16 v[58:61], v[100:103], v[164:167], v[58:61]
	v_mfma_f32_16x16x32_bf16 v[46:49], v[90:93], v[172:175], v[46:49]
	v_mfma_f32_16x16x32_bf16 v[42:45], v[100:103], v[172:175], v[42:45]
	v_mfma_f32_16x16x32_bf16 v[30:33], v[90:93], v[180:183], v[30:33]
	v_mfma_f32_16x16x32_bf16 v[26:29], v[100:103], v[180:183], v[26:29]
	v_mfma_f32_16x16x32_bf16 v[14:17], v[90:93], v[188:191], v[14:17]
	v_mfma_f32_16x16x32_bf16 v[10:13], v[100:103], v[188:191], v[10:13]
	v_mfma_f32_16x16x32_bf16 v[62:65], v[94:97], v[168:171], v[62:65]
	v_mfma_f32_16x16x32_bf16 v[58:61], v[104:107], v[168:171], v[58:61]
	v_mfma_f32_16x16x32_bf16 v[46:49], v[94:97], v[176:179], v[46:49]
	v_mfma_f32_16x16x32_bf16 v[42:45], v[104:107], v[176:179], v[42:45]
	v_mfma_f32_16x16x32_bf16 v[30:33], v[94:97], v[184:187], v[30:33]
	v_mfma_f32_16x16x32_bf16 v[26:29], v[104:107], v[184:187], v[26:29]
	v_mfma_f32_16x16x32_bf16 v[14:17], v[94:97], v[192:195], v[14:17]
	v_mfma_f32_16x16x32_bf16 v[10:13], v[104:107], v[192:195], v[10:13]
	s_setprio 0
	s_setprio 1
	v_mfma_f32_16x16x32_bf16 v[54:57], v[108:111], v[164:167], v[54:57]
	v_mfma_f32_16x16x32_bf16 v[50:53], v[120:123], v[164:167], v[50:53]
	v_mfma_f32_16x16x32_bf16 v[38:41], v[108:111], v[172:175], v[38:41]
	v_mfma_f32_16x16x32_bf16 v[34:37], v[120:123], v[172:175], v[34:37]
	v_mfma_f32_16x16x32_bf16 v[22:25], v[108:111], v[180:183], v[22:25]
	v_mfma_f32_16x16x32_bf16 v[18:21], v[120:123], v[180:183], v[18:21]
	v_mfma_f32_16x16x32_bf16 v[6:9], v[108:111], v[188:191], v[6:9]
	v_mfma_f32_16x16x32_bf16 v[2:5], v[120:123], v[188:191], v[2:5]
	v_mfma_f32_16x16x32_bf16 v[54:57], v[112:115], v[168:171], v[54:57]
	v_mfma_f32_16x16x32_bf16 v[50:53], v[128:131], v[168:171], v[50:53]
	v_mfma_f32_16x16x32_bf16 v[38:41], v[112:115], v[176:179], v[38:41]
	v_mfma_f32_16x16x32_bf16 v[34:37], v[128:131], v[176:179], v[34:37]
	v_mfma_f32_16x16x32_bf16 v[22:25], v[112:115], v[184:187], v[22:25]
	v_mfma_f32_16x16x32_bf16 v[18:21], v[128:131], v[184:187], v[18:21]
	v_mfma_f32_16x16x32_bf16 v[6:9], v[112:115], v[192:195], v[6:9]
	v_mfma_f32_16x16x32_bf16 v[2:5], v[128:131], v[192:195], v[2:5]
	s_setprio 0
	s_barrier
	s_mov_b32 s100, 0
	s_add_i32 s97, s97, 2
	s_add_u32 s68, s68, 0x100
	s_addc_u32 s69, s69, 0
	s_add_u32 vcc_hi, vcc_hi, 0x100
	s_addc_u32 s96, s96, 0
	s_cmp_gt_u32 s97, 13
	s_cbranch_scc0 .LBB0_864
	s_mov_b32 s100, 1
	s_and_b64 vcc, exec, s[12:13]
	s_cbranch_vccz .LBB0_867
	s_barrier

.Lmy_sk5:
	s_waitcnt lgkmcnt(0)
	s_setprio 1
	s_barrier
	v_mfma_f32_16x16x32_bf16 v[160:163], v[86:89], v[164:167], v[160:163]
	v_mfma_f32_16x16x32_bf16 v[156:159], v[100:103], v[164:167], v[156:159]
	v_mfma_f32_16x16x32_bf16 v[144:147], v[86:89], v[172:175], v[144:147]
	v_mfma_f32_16x16x32_bf16 v[140:143], v[100:103], v[172:175], v[140:143]
	v_mfma_f32_16x16x32_bf16 v[128:131], v[86:89], v[180:183], v[128:131]
	v_mfma_f32_16x16x32_bf16 v[120:123], v[100:103], v[180:183], v[120:123]
	v_mfma_f32_16x16x32_bf16 v[78:81], v[86:89], v[188:191], v[78:81]
	v_mfma_f32_16x16x32_bf16 v[74:77], v[100:103], v[188:191], v[74:77]
	v_mfma_f32_16x16x32_bf16 v[160:163], v[90:93], v[168:171], v[160:163]
	v_mfma_f32_16x16x32_bf16 v[156:159], v[104:107], v[168:171], v[156:159]
	v_mfma_f32_16x16x32_bf16 v[144:147], v[90:93], v[176:179], v[144:147]
	v_mfma_f32_16x16x32_bf16 v[140:143], v[104:107], v[176:179], v[140:143]
	v_mfma_f32_16x16x32_bf16 v[128:131], v[90:93], v[184:187], v[128:131]
	v_mfma_f32_16x16x32_bf16 v[120:123], v[104:107], v[184:187], v[120:123]
	v_mfma_f32_16x16x32_bf16 v[78:81], v[90:93], v[192:195], v[78:81]
	v_mfma_f32_16x16x32_bf16 v[74:77], v[104:107], v[192:195], v[74:77]
	s_setprio 0
	s_setprio 1
	v_mfma_f32_16x16x32_bf16 v[152:155], v[108:111], v[164:167], v[152:155]
	v_mfma_f32_16x16x32_bf16 v[148:151], v[116:119], v[164:167], v[148:151]
	v_mfma_f32_16x16x32_bf16 v[136:139], v[108:111], v[172:175], v[136:139]
	v_mfma_f32_16x16x32_bf16 v[132:135], v[116:119], v[172:175], v[132:135]
	v_mfma_f32_16x16x32_bf16 v[94:97], v[108:111], v[180:183], v[94:97]
	v_mfma_f32_16x16x32_bf16 v[82:85], v[116:119], v[180:183], v[82:85]
	v_mfma_f32_16x16x32_bf16 v[70:73], v[108:111], v[188:191], v[70:73]
	v_mfma_f32_16x16x32_bf16 v[66:69], v[116:119], v[188:191], v[66:69]
	v_mfma_f32_16x16x32_bf16 v[152:155], v[112:115], v[168:171], v[152:155]
	v_mfma_f32_16x16x32_bf16 v[148:151], v[124:127], v[168:171], v[148:151]
	v_mfma_f32_16x16x32_bf16 v[136:139], v[112:115], v[176:179], v[136:139]
	v_mfma_f32_16x16x32_bf16 v[132:135], v[124:127], v[176:179], v[132:135]
	v_mfma_f32_16x16x32_bf16 v[94:97], v[112:115], v[184:187], v[94:97]
	v_mfma_f32_16x16x32_bf16 v[82:85], v[124:127], v[184:187], v[82:85]
	v_mfma_f32_16x16x32_bf16 v[70:73], v[112:115], v[192:195], v[70:73]
	v_mfma_f32_16x16x32_bf16 v[66:69], v[124:127], v[192:195], v[66:69]
	s_setprio 0
	s_barrier
	s_add_i32 s4, s45, s74
	v_lshl_add_u64 v[200:201], s[68:69], 0, v[204:205]
	s_mov_b32 m0, s4
	ds_read_b128 v[164:167], v225 offset:16384
	ds_read_b128 v[168:171], v225 offset:17408
	ds_read_b128 v[172:175], v225 offset:18432
	ds_read_b128 v[176:179], v225 offset:19456
	ds_read_b128 v[180:183], v225 offset:20480
	ds_read_b128 v[184:187], v225 offset:21504
	ds_read_b128 v[188:191], v225 offset:22528
	ds_read_b128 v[192:195], v225 offset:23552
	global_load_lds_dwordx4 v[200:201], off
	s_add_i32 m0, s4, 0x2000
	s_add_u32 s4, s68, 0x40000
	v_lshl_add_u64 v[202:203], s[68:69], 0, v[208:209]
	s_addc_u32 s5, s69, 0
	s_add_i32 s45, s97, s74
	global_load_lds_dwordx4 v[202:203], off
	v_lshl_add_u64 v[210:211], s[4:5], 0, v[204:205]
	s_mov_b32 m0, s45
	v_lshl_add_u64 v[212:213], s[70:71], 0, v[206:207]
	global_load_lds_dwordx4 v[210:211], off
	v_lshl_add_u64 v[210:211], s[4:5], 0, v[208:209]
	s_add_i32 m0, s45, 0x2000
	s_nop 0
	global_load_lds_dwordx4 v[210:211], off
	v_lshl_add_u64 v[210:211], s[70:71], 0, v[98:99]
	s_mov_b32 m0, s44
	s_nop 0
	global_load_lds_dwordx4 v[210:211], off
	s_add_i32 m0, s44, 0x2000
	s_nop 0
	global_load_lds_dwordx4 v[212:213], off
	s_cmp_eq_u32 s100, 1
	s_cbranch_scc1 .Lmy_sk6
	s_waitcnt vmcnt(8)
.Lmy_sk6:
	s_waitcnt lgkmcnt(0)
	s_setprio 1
	s_barrier
	v_mfma_f32_16x16x32_bf16 v[62:65], v[86:89], v[164:167], v[62:65]
	v_mfma_f32_16x16x32_bf16 v[58:61], v[100:103], v[164:167], v[58:61]
	v_mfma_f32_16x16x32_bf16 v[46:49], v[86:89], v[172:175], v[46:49]
	v_mfma_f32_16x16x32_bf16 v[42:45], v[100:103], v[172:175], v[42:45]
	v_mfma_f32_16x16x32_bf16 v[30:33], v[86:89], v[180:183], v[30:33]
	v_mfma_f32_16x16x32_bf16 v[26:29], v[100:103], v[180:183], v[26:29]
	v_mfma_f32_16x16x32_bf16 v[14:17], v[86:89], v[188:191], v[14:17]
	v_mfma_f32_16x16x32_bf16 v[10:13], v[100:103], v[188:191], v[10:13]
	v_mfma_f32_16x16x32_bf16 v[62:65], v[90:93], v[168:171], v[62:65]
	v_mfma_f32_16x16x32_bf16 v[58:61], v[104:107], v[168:171], v[58:61]
	v_mfma_f32_16x16x32_bf16 v[46:49], v[90:93], v[176:179], v[46:49]
	v_mfma_f32_16x16x32_bf16 v[42:45], v[104:107], v[176:179], v[42:45]
	v_mfma_f32_16x16x32_bf16 v[30:33], v[90:93], v[184:187], v[30:33]
	v_mfma_f32_16x16x32_bf16 v[26:29], v[104:107], v[184:187], v[26:29]
	v_mfma_f32_16x16x32_bf16 v[14:17], v[90:93], v[192:195], v[14:17]
	v_mfma_f32_16x16x32_bf16 v[10:13], v[104:107], v[192:195], v[10:13]
	s_setprio 0
	s_setprio 1
	v_mfma_f32_16x16x32_bf16 v[54:57], v[108:111], v[164:167], v[54:57]
	v_mfma_f32_16x16x32_bf16 v[50:53], v[116:119], v[164:167], v[50:53]
	v_mfma_f32_16x16x32_bf16 v[38:41], v[108:111], v[172:175], v[38:41]
	v_mfma_f32_16x16x32_bf16 v[34:37], v[116:119], v[172:175], v[34:37]
	v_mfma_f32_16x16x32_bf16 v[22:25], v[108:111], v[180:183], v[22:25]
	v_mfma_f32_16x16x32_bf16 v[18:21], v[116:119], v[180:183], v[18:21]
	v_mfma_f32_16x16x32_bf16 v[6:9], v[108:111], v[188:191], v[6:9]
	v_mfma_f32_16x16x32_bf16 v[2:5], v[116:119], v[188:191], v[2:5]
	v_mfma_f32_16x16x32_bf16 v[54:57], v[112:115], v[168:171], v[54:57]
	v_mfma_f32_16x16x32_bf16 v[50:53], v[124:127], v[168:171], v[50:53]
	v_mfma_f32_16x16x32_bf16 v[38:41], v[112:115], v[176:179], v[38:41]
	v_mfma_f32_16x16x32_bf16 v[34:37], v[124:127], v[176:179], v[34:37]
	v_mfma_f32_16x16x32_bf16 v[22:25], v[112:115], v[184:187], v[22:25]
	v_mfma_f32_16x16x32_bf16 v[18:21], v[124:127], v[184:187], v[18:21]
	v_mfma_f32_16x16x32_bf16 v[6:9], v[112:115], v[192:195], v[6:9]
	v_mfma_f32_16x16x32_bf16 v[2:5], v[124:127], v[192:195], v[2:5]
	s_setprio 0
	s_barrier
	s_add_i32 s45, 0, 0x18000
	s_add_i32 s97, 0, 0x1c000
	v_add_u32_e32 v104, s45, v223
	v_add_u32_e32 v124, s97, v223
	ds_read_b128 v[86:89], v104
	ds_read_b128 v[90:93], v104 offset:1024
	ds_read_b128 v[100:103], v104 offset:2048
	ds_read_b128 v[104:107], v104 offset:3072
	ds_read_b128 v[108:111], v124
	ds_read_b128 v[112:115], v124 offset:1024
	ds_read_b128 v[116:119], v124 offset:2048
	ds_read_b128 v[124:127], v124 offset:3072
	s_add_u32 s4, s70, 0x40000
	s_addc_u32 s5, s71, 0
	v_lshl_add_u64 v[214:215], s[4:5], 0, v[98:99]
	s_add_i32 m0, s44, 0x4000
	ds_read_b128 v[164:167], v225 offset:32768
	ds_read_b128 v[168:171], v225 offset:33792
	ds_read_b128 v[172:175], v225 offset:34816
	ds_read_b128 v[176:179], v225 offset:35840
	ds_read_b128 v[180:183], v225 offset:36864
	ds_read_b128 v[184:187], v225 offset:37888
	ds_read_b128 v[188:191], v225 offset:38912
	ds_read_b128 v[192:195], v225 offset:39936
	global_load_lds_dwordx4 v[214:215], off
	v_lshl_add_u64 v[214:215], s[4:5], 0, v[206:207]
	s_add_i32 m0, s44, 0x6000
	s_nop 0
	global_load_lds_dwordx4 v[214:215], off
	s_waitcnt vmcnt(8)
	s_waitcnt lgkmcnt(0)
	s_setprio 1
	s_barrier
	v_mfma_f32_16x16x32_bf16 v[160:163], v[86:89], v[164:167], v[160:163]
	v_mfma_f32_16x16x32_bf16 v[156:159], v[100:103], v[164:167], v[156:159]
	v_mfma_f32_16x16x32_bf16 v[144:147], v[86:89], v[172:175], v[144:147]
	v_mfma_f32_16x16x32_bf16 v[140:143], v[100:103], v[172:175], v[140:143]
	v_mfma_f32_16x16x32_bf16 v[128:131], v[86:89], v[180:183], v[128:131]
	v_mfma_f32_16x16x32_bf16 v[120:123], v[100:103], v[180:183], v[120:123]
	v_mfma_f32_16x16x32_bf16 v[78:81], v[86:89], v[188:191], v[78:81]
	v_mfma_f32_16x16x32_bf16 v[74:77], v[100:103], v[188:191], v[74:77]
	v_mfma_f32_16x16x32_bf16 v[160:163], v[90:93], v[168:171], v[160:163]
	v_mfma_f32_16x16x32_bf16 v[156:159], v[104:107], v[168:171], v[156:159]
	v_mfma_f32_16x16x32_bf16 v[144:147], v[90:93], v[176:179], v[144:147]
	v_mfma_f32_16x16x32_bf16 v[140:143], v[104:107], v[176:179], v[140:143]
	v_mfma_f32_16x16x32_bf16 v[128:131], v[90:93], v[184:187], v[128:131]
	v_mfma_f32_16x16x32_bf16 v[120:123], v[104:107], v[184:187], v[120:123]
	v_mfma_f32_16x16x32_bf16 v[78:81], v[90:93], v[192:195], v[78:81]
	v_mfma_f32_16x16x32_bf16 v[74:77], v[104:107], v[192:195], v[74:77]
	s_setprio 0
	s_setprio 1
	v_mfma_f32_16x16x32_bf16 v[152:155], v[108:111], v[164:167], v[152:155]
	v_mfma_f32_16x16x32_bf16 v[148:151], v[116:119], v[164:167], v[148:151]
	v_mfma_f32_16x16x32_bf16 v[136:139], v[108:111], v[172:175], v[136:139]
	v_mfma_f32_16x16x32_bf16 v[132:135], v[116:119], v[172:175], v[132:135]
	v_mfma_f32_16x16x32_bf16 v[94:97], v[108:111], v[180:183], v[94:97]
	v_mfma_f32_16x16x32_bf16 v[82:85], v[116:119], v[180:183], v[82:85]
	v_mfma_f32_16x16x32_bf16 v[70:73], v[108:111], v[188:191], v[70:73]
	v_mfma_f32_16x16x32_bf16 v[66:69], v[116:119], v[188:191], v[66:69]
	v_mfma_f32_16x16x32_bf16 v[152:155], v[112:115], v[168:171], v[152:155]
	v_mfma_f32_16x16x32_bf16 v[148:151], v[124:127], v[168:171], v[148:151]
	v_mfma_f32_16x16x32_bf16 v[136:139], v[112:115], v[176:179], v[136:139]
	v_mfma_f32_16x16x32_bf16 v[132:135], v[124:127], v[176:179], v[132:135]
	v_mfma_f32_16x16x32_bf16 v[94:97], v[112:115], v[184:187], v[94:97]
	v_mfma_f32_16x16x32_bf16 v[82:85], v[124:127], v[184:187], v[82:85]
	v_mfma_f32_16x16x32_bf16 v[70:73], v[112:115], v[192:195], v[70:73]
	v_mfma_f32_16x16x32_bf16 v[66:69], v[124:127], v[192:195], v[66:69]
	s_setprio 0
	s_barrier
	s_add_i32 s4, s45, s74
	v_lshl_add_u64 v[200:201], v[200:201], 0, s[42:43]
	s_mov_b32 m0, s4
	ds_read_b128 v[164:167], v225 offset:49152
	ds_read_b128 v[168:171], v225 offset:50176
	ds_read_b128 v[172:175], v225 offset:51200
	ds_read_b128 v[176:179], v225 offset:52224
	ds_read_b128 v[180:183], v225 offset:53248
	ds_read_b128 v[184:187], v225 offset:54272
	ds_read_b128 v[188:191], v225 offset:55296
	ds_read_b128 v[192:195], v225 offset:56320
	global_load_lds_dwordx4 v[200:201], off
	s_add_i32 m0, s4, 0x2000
	s_add_u32 s4, s68, 0x40080
	v_lshl_add_u64 v[200:201], v[202:203], 0, s[42:43]
	s_addc_u32 s5, s69, 0
	s_add_i32 s45, s97, s74
	global_load_lds_dwordx4 v[200:201], off
	v_lshl_add_u64 v[200:201], s[4:5], 0, v[204:205]
	s_mov_b32 m0, s45
	s_nop 0
	global_load_lds_dwordx4 v[200:201], off
	v_lshl_add_u64 v[200:201], s[4:5], 0, v[208:209]
	s_add_i32 m0, s45, 0x2000
	s_nop 0
	global_load_lds_dwordx4 v[200:201], off
	v_lshl_add_u64 v[200:201], v[210:211], 0, s[42:43]
	s_add_i32 m0, s44, 0x8000
	s_nop 0
	global_load_lds_dwordx4 v[200:201], off
	v_lshl_add_u64 v[200:201], v[212:213], 0, s[42:43]
	s_add_i32 m0, s44, 0xa000
	s_nop 0
	global_load_lds_dwordx4 v[200:201], off
	s_waitcnt vmcnt(8)
	s_waitcnt lgkmcnt(0)
	s_setprio 1
	s_barrier
	v_mfma_f32_16x16x32_bf16 v[62:65], v[86:89], v[164:167], v[62:65]
	v_mfma_f32_16x16x32_bf16 v[58:61], v[100:103], v[164:167], v[58:61]
	v_mfma_f32_16x16x32_bf16 v[46:49], v[86:89], v[172:175], v[46:49]
	v_mfma_f32_16x16x32_bf16 v[42:45], v[100:103], v[172:175], v[42:45]
	v_mfma_f32_16x16x32_bf16 v[30:33], v[86:89], v[180:183], v[30:33]
	v_mfma_f32_16x16x32_bf16 v[26:29], v[100:103], v[180:183], v[26:29]
	v_mfma_f32_16x16x32_bf16 v[14:17], v[86:89], v[188:191], v[14:17]
	v_mfma_f32_16x16x32_bf16 v[10:13], v[100:103], v[188:191], v[10:13]
	v_mfma_f32_16x16x32_bf16 v[62:65], v[90:93], v[168:171], v[62:65]
	v_mfma_f32_16x16x32_bf16 v[58:61], v[104:107], v[168:171], v[58:61]
	v_mfma_f32_16x16x32_bf16 v[46:49], v[90:93], v[176:179], v[46:49]
	v_mfma_f32_16x16x32_bf16 v[42:45], v[104:107], v[176:179], v[42:45]
	v_mfma_f32_16x16x32_bf16 v[30:33], v[90:93], v[184:187], v[30:33]
	v_mfma_f32_16x16x32_bf16 v[26:29], v[104:107], v[184:187], v[26:29]
	v_mfma_f32_16x16x32_bf16 v[14:17], v[90:93], v[192:195], v[14:17]
	v_mfma_f32_16x16x32_bf16 v[10:13], v[104:107], v[192:195], v[10:13]
	s_setprio 0
	s_setprio 1
	v_mfma_f32_16x16x32_bf16 v[54:57], v[108:111], v[164:167], v[54:57]
	v_mfma_f32_16x16x32_bf16 v[50:53], v[116:119], v[164:167], v[50:53]
	v_mfma_f32_16x16x32_bf16 v[38:41], v[108:111], v[172:175], v[38:41]
	v_mfma_f32_16x16x32_bf16 v[34:37], v[116:119], v[172:175], v[34:37]
	v_mfma_f32_16x16x32_bf16 v[22:25], v[108:111], v[180:183], v[22:25]
	v_mfma_f32_16x16x32_bf16 v[18:21], v[116:119], v[180:183], v[18:21]
	v_mfma_f32_16x16x32_bf16 v[6:9], v[108:111], v[188:191], v[6:9]
	v_mfma_f32_16x16x32_bf16 v[2:5], v[116:119], v[188:191], v[2:5]
	v_mfma_f32_16x16x32_bf16 v[54:57], v[112:115], v[168:171], v[54:57]
	v_mfma_f32_16x16x32_bf16 v[50:53], v[124:127], v[168:171], v[50:53]
	v_mfma_f32_16x16x32_bf16 v[38:41], v[112:115], v[176:179], v[38:41]
	v_mfma_f32_16x16x32_bf16 v[34:37], v[124:127], v[176:179], v[34:37]
	v_mfma_f32_16x16x32_bf16 v[22:25], v[112:115], v[184:187], v[22:25]
	v_mfma_f32_16x16x32_bf16 v[18:21], v[124:127], v[184:187], v[18:21]
	v_mfma_f32_16x16x32_bf16 v[6:9], v[112:115], v[192:195], v[6:9]
	v_mfma_f32_16x16x32_bf16 v[2:5], v[124:127], v[192:195], v[2:5]
	s_setprio 0
	s_barrier
	s_mov_b32 s100, 0
	s_add_i32 s96, s96, 2
	s_add_u32 s56, s56, 0x100
	s_addc_u32 s57, s57, 0
	s_add_u32 s95, s95, 0x100
	s_addc_u32 vcc_lo, vcc_lo, 0
	s_cmp_gt_u32 s96, 13
	s_cbranch_scc0 .LBB0_908
	s_mov_b32 s100, 1
	v_mov_b32_e32 v196, 0x2d00
	v_mov_b32_e32 v231, 0x2400
	v_mov_b32_e32 v228, 0x1b00
	s_and_b64 vcc, exec, s[0:1]
	s_movk_i32 s21, 0x4000
	s_cbranch_vccz .LBB0_911
	s_barrier

.Lmy_sk7:
	s_waitcnt lgkmcnt(0)
	s_setprio 1
	s_barrier
	v_mfma_f32_16x16x32_bf16 v[128:131], v[132:135], v[204:207], v[128:131]
	v_mfma_f32_16x16x32_bf16 v[124:127], v[140:143], v[204:207], v[124:127]
	v_mfma_f32_16x16x32_bf16 v[112:115], v[132:135], v[212:215], v[112:115]
	v_mfma_f32_16x16x32_bf16 v[108:111], v[140:143], v[212:215], v[108:111]
	v_mfma_f32_16x16x32_bf16 v[94:97], v[132:135], v[220:223], v[94:97]
	v_mfma_f32_16x16x32_bf16 v[90:93], v[140:143], v[220:223], v[90:93]
	v_mfma_f32_16x16x32_bf16 v[78:81], v[132:135], v[238:241], v[78:81]
	v_mfma_f32_16x16x32_bf16 v[74:77], v[140:143], v[238:241], v[74:77]
	v_mfma_f32_16x16x32_bf16 v[128:131], v[136:139], v[208:211], v[128:131]
	v_mfma_f32_16x16x32_bf16 v[124:127], v[144:147], v[208:211], v[124:127]
	v_mfma_f32_16x16x32_bf16 v[112:115], v[136:139], v[216:219], v[112:115]
	v_mfma_f32_16x16x32_bf16 v[108:111], v[144:147], v[216:219], v[108:111]
	v_mfma_f32_16x16x32_bf16 v[94:97], v[136:139], v[224:227], v[94:97]
	v_mfma_f32_16x16x32_bf16 v[90:93], v[144:147], v[224:227], v[90:93]
	v_mfma_f32_16x16x32_bf16 v[78:81], v[136:139], v[242:245], v[78:81]
	v_mfma_f32_16x16x32_bf16 v[74:77], v[144:147], v[242:245], v[74:77]
	s_setprio 0
	s_setprio 1
	v_mfma_f32_16x16x32_bf16 v[120:123], v[156:159], v[204:207], v[120:123]
	v_mfma_f32_16x16x32_bf16 v[116:119], v[192:195], v[204:207], v[116:119]
	v_mfma_f32_16x16x32_bf16 v[104:107], v[156:159], v[212:215], v[104:107]
	v_mfma_f32_16x16x32_bf16 v[100:103], v[192:195], v[212:215], v[100:103]
	v_mfma_f32_16x16x32_bf16 v[86:89], v[156:159], v[220:223], v[86:89]
	v_mfma_f32_16x16x32_bf16 v[82:85], v[192:195], v[220:223], v[82:85]
	v_mfma_f32_16x16x32_bf16 v[70:73], v[156:159], v[238:241], v[70:73]
	v_mfma_f32_16x16x32_bf16 v[66:69], v[192:195], v[238:241], v[66:69]
	v_mfma_f32_16x16x32_bf16 v[120:123], v[162:165], v[208:211], v[120:123]
	v_mfma_f32_16x16x32_bf16 v[116:119], v[200:203], v[208:211], v[116:119]
	v_mfma_f32_16x16x32_bf16 v[104:107], v[162:165], v[216:219], v[104:107]
	v_mfma_f32_16x16x32_bf16 v[100:103], v[200:203], v[216:219], v[100:103]
	v_mfma_f32_16x16x32_bf16 v[86:89], v[162:165], v[224:227], v[86:89]
	v_mfma_f32_16x16x32_bf16 v[82:85], v[200:203], v[224:227], v[82:85]
	v_mfma_f32_16x16x32_bf16 v[70:73], v[162:165], v[242:245], v[70:73]
	v_mfma_f32_16x16x32_bf16 v[66:69], v[200:203], v[242:245], v[66:69]
	s_setprio 0
	s_barrier
	s_add_i32 s4, s6, s70
	v_lshl_add_u64 v[166:167], s[56:57], 0, v[148:149]
	s_mov_b32 m0, s4
	ds_read_b128 v[204:207], v191 offset:16384
	ds_read_b128 v[208:211], v191 offset:17408
	ds_read_b128 v[212:215], v191 offset:18432
	ds_read_b128 v[216:219], v191 offset:19456
	ds_read_b128 v[220:223], v191 offset:20480
	ds_read_b128 v[224:227], v191 offset:21504
	ds_read_b128 v[238:241], v191 offset:22528
	ds_read_b128 v[242:245], v191 offset:23552
	global_load_lds_dwordx4 v[166:167], off
	s_add_i32 m0, s4, 0x2000
	s_add_u32 s4, s56, 0x40000
	v_lshl_add_u64 v[170:171], s[56:57], 0, v[152:153]
	s_addc_u32 s5, s57, 0
	s_add_i32 s6, s7, s70
	global_load_lds_dwordx4 v[170:171], off
	v_lshl_add_u64 v[176:177], s[4:5], 0, v[148:149]
	s_mov_b32 m0, s6
	v_lshl_add_u64 v[180:181], s[68:69], 0, v[150:151]
	global_load_lds_dwordx4 v[176:177], off
	v_lshl_add_u64 v[176:177], s[4:5], 0, v[152:153]
	s_add_i32 m0, s6, 0x2000
	s_nop 0
	global_load_lds_dwordx4 v[176:177], off
	v_lshl_add_u64 v[176:177], s[68:69], 0, v[98:99]
	s_mov_b32 m0, s44
	s_nop 0
	global_load_lds_dwordx4 v[176:177], off
	s_add_i32 m0, s44, 0x2000
	s_nop 0
	global_load_lds_dwordx4 v[180:181], off
	s_cmp_eq_u32 s100, 1
	s_cbranch_scc1 .Lmy_sk8
	s_waitcnt vmcnt(8)
.Lmy_sk8:
	s_waitcnt lgkmcnt(0)
	s_setprio 1
	s_barrier
	v_mfma_f32_16x16x32_bf16 v[62:65], v[132:135], v[204:207], v[62:65]
	v_mfma_f32_16x16x32_bf16 v[58:61], v[140:143], v[204:207], v[58:61]
	v_mfma_f32_16x16x32_bf16 v[46:49], v[132:135], v[212:215], v[46:49]
	v_mfma_f32_16x16x32_bf16 v[42:45], v[140:143], v[212:215], v[42:45]
	v_mfma_f32_16x16x32_bf16 v[30:33], v[132:135], v[220:223], v[30:33]
	v_mfma_f32_16x16x32_bf16 v[26:29], v[140:143], v[220:223], v[26:29]
	v_mfma_f32_16x16x32_bf16 v[14:17], v[132:135], v[238:241], v[14:17]
	v_mfma_f32_16x16x32_bf16 v[10:13], v[140:143], v[238:241], v[10:13]
	v_mfma_f32_16x16x32_bf16 v[62:65], v[136:139], v[208:211], v[62:65]
	v_mfma_f32_16x16x32_bf16 v[58:61], v[144:147], v[208:211], v[58:61]
	v_mfma_f32_16x16x32_bf16 v[46:49], v[136:139], v[216:219], v[46:49]
	v_mfma_f32_16x16x32_bf16 v[42:45], v[144:147], v[216:219], v[42:45]
	v_mfma_f32_16x16x32_bf16 v[30:33], v[136:139], v[224:227], v[30:33]
	v_mfma_f32_16x16x32_bf16 v[26:29], v[144:147], v[224:227], v[26:29]
	v_mfma_f32_16x16x32_bf16 v[14:17], v[136:139], v[242:245], v[14:17]
	v_mfma_f32_16x16x32_bf16 v[10:13], v[144:147], v[242:245], v[10:13]
	s_setprio 0
	s_setprio 1
	v_mfma_f32_16x16x32_bf16 v[54:57], v[156:159], v[204:207], v[54:57]
	v_mfma_f32_16x16x32_bf16 v[50:53], v[192:195], v[204:207], v[50:53]
	v_mfma_f32_16x16x32_bf16 v[38:41], v[156:159], v[212:215], v[38:41]
	v_mfma_f32_16x16x32_bf16 v[34:37], v[192:195], v[212:215], v[34:37]
	v_mfma_f32_16x16x32_bf16 v[22:25], v[156:159], v[220:223], v[22:25]
	v_mfma_f32_16x16x32_bf16 v[18:21], v[192:195], v[220:223], v[18:21]
	v_mfma_f32_16x16x32_bf16 v[6:9], v[156:159], v[238:241], v[6:9]
	v_mfma_f32_16x16x32_bf16 v[2:5], v[192:195], v[238:241], v[2:5]
	v_mfma_f32_16x16x32_bf16 v[54:57], v[162:165], v[208:211], v[54:57]
	v_mfma_f32_16x16x32_bf16 v[50:53], v[200:203], v[208:211], v[50:53]
	v_mfma_f32_16x16x32_bf16 v[38:41], v[162:165], v[216:219], v[38:41]
	v_mfma_f32_16x16x32_bf16 v[34:37], v[200:203], v[216:219], v[34:37]
	v_mfma_f32_16x16x32_bf16 v[22:25], v[162:165], v[224:227], v[22:25]
	v_mfma_f32_16x16x32_bf16 v[18:21], v[200:203], v[224:227], v[18:21]
	v_mfma_f32_16x16x32_bf16 v[6:9], v[162:165], v[242:245], v[6:9]
	v_mfma_f32_16x16x32_bf16 v[2:5], v[200:203], v[242:245], v[2:5]
	s_setprio 0
	s_barrier
	s_add_i32 s6, 0, 0x18000
	s_add_i32 s7, 0, 0x1c000
	v_add_u32_e32 v144, s6, v189
	v_add_u32_e32 v160, s7, v189
	ds_read_b128 v[132:135], v144
	ds_read_b128 v[136:139], v144 offset:1024
	ds_read_b128 v[140:143], v144 offset:2048
	ds_read_b128 v[144:147], v144 offset:3072
	ds_read_b128 v[156:159], v160
	ds_read_b128 v[162:165], v160 offset:1024
	ds_read_b128 v[192:195], v160 offset:2048
	ds_read_b128 v[200:203], v160 offset:3072
	s_add_u32 s4, s68, 0x40000
	s_addc_u32 s5, s69, 0
	v_lshl_add_u64 v[246:247], s[4:5], 0, v[98:99]
	s_add_i32 m0, s44, 0x4000
	ds_read_b128 v[204:207], v191 offset:32768
	ds_read_b128 v[208:211], v191 offset:33792
	ds_read_b128 v[212:215], v191 offset:34816
	ds_read_b128 v[216:219], v191 offset:35840
	ds_read_b128 v[220:223], v191 offset:36864
	ds_read_b128 v[224:227], v191 offset:37888
	ds_read_b128 v[238:241], v191 offset:38912
	ds_read_b128 v[242:245], v191 offset:39936
	global_load_lds_dwordx4 v[246:247], off
	v_lshl_add_u64 v[246:247], s[4:5], 0, v[150:151]
	s_add_i32 m0, s44, 0x6000
	s_nop 0
	global_load_lds_dwordx4 v[246:247], off
	s_waitcnt vmcnt(8)
	s_waitcnt lgkmcnt(0)
	s_setprio 1
	s_barrier
	v_mfma_f32_16x16x32_bf16 v[128:131], v[132:135], v[204:207], v[128:131]
	v_mfma_f32_16x16x32_bf16 v[124:127], v[140:143], v[204:207], v[124:127]
	v_mfma_f32_16x16x32_bf16 v[112:115], v[132:135], v[212:215], v[112:115]
	v_mfma_f32_16x16x32_bf16 v[108:111], v[140:143], v[212:215], v[108:111]
	v_mfma_f32_16x16x32_bf16 v[94:97], v[132:135], v[220:223], v[94:97]
	v_mfma_f32_16x16x32_bf16 v[90:93], v[140:143], v[220:223], v[90:93]
	v_mfma_f32_16x16x32_bf16 v[78:81], v[132:135], v[238:241], v[78:81]
	v_mfma_f32_16x16x32_bf16 v[74:77], v[140:143], v[238:241], v[74:77]
	v_mfma_f32_16x16x32_bf16 v[128:131], v[136:139], v[208:211], v[128:131]
	v_mfma_f32_16x16x32_bf16 v[124:127], v[144:147], v[208:211], v[124:127]
	v_mfma_f32_16x16x32_bf16 v[112:115], v[136:139], v[216:219], v[112:115]
	v_mfma_f32_16x16x32_bf16 v[108:111], v[144:147], v[216:219], v[108:111]
	v_mfma_f32_16x16x32_bf16 v[94:97], v[136:139], v[224:227], v[94:97]
	v_mfma_f32_16x16x32_bf16 v[90:93], v[144:147], v[224:227], v[90:93]
	v_mfma_f32_16x16x32_bf16 v[78:81], v[136:139], v[242:245], v[78:81]
	v_mfma_f32_16x16x32_bf16 v[74:77], v[144:147], v[242:245], v[74:77]
	s_setprio 0
	s_setprio 1
	v_mfma_f32_16x16x32_bf16 v[120:123], v[156:159], v[204:207], v[120:123]
	v_mfma_f32_16x16x32_bf16 v[116:119], v[192:195], v[204:207], v[116:119]
	v_mfma_f32_16x16x32_bf16 v[104:107], v[156:159], v[212:215], v[104:107]
	v_mfma_f32_16x16x32_bf16 v[100:103], v[192:195], v[212:215], v[100:103]
	v_mfma_f32_16x16x32_bf16 v[86:89], v[156:159], v[220:223], v[86:89]
	v_mfma_f32_16x16x32_bf16 v[82:85], v[192:195], v[220:223], v[82:85]
	v_mfma_f32_16x16x32_bf16 v[70:73], v[156:159], v[238:241], v[70:73]
	v_mfma_f32_16x16x32_bf16 v[66:69], v[192:195], v[238:241], v[66:69]
	v_mfma_f32_16x16x32_bf16 v[120:123], v[162:165], v[208:211], v[120:123]
	v_mfma_f32_16x16x32_bf16 v[116:119], v[200:203], v[208:211], v[116:119]
	v_mfma_f32_16x16x32_bf16 v[104:107], v[162:165], v[216:219], v[104:107]
	v_mfma_f32_16x16x32_bf16 v[100:103], v[200:203], v[216:219], v[100:103]
	v_mfma_f32_16x16x32_bf16 v[86:89], v[162:165], v[224:227], v[86:89]
	v_mfma_f32_16x16x32_bf16 v[82:85], v[200:203], v[224:227], v[82:85]
	v_mfma_f32_16x16x32_bf16 v[70:73], v[162:165], v[242:245], v[70:73]
	v_mfma_f32_16x16x32_bf16 v[66:69], v[200:203], v[242:245], v[66:69]
	s_setprio 0
	s_barrier
	s_add_i32 s4, s6, s70
	v_lshl_add_u64 v[166:167], v[166:167], 0, s[42:43]
	s_mov_b32 m0, s4
	ds_read_b128 v[204:207], v191 offset:49152
	ds_read_b128 v[208:211], v191 offset:50176
	ds_read_b128 v[212:215], v191 offset:51200
	ds_read_b128 v[216:219], v191 offset:52224
	ds_read_b128 v[220:223], v191 offset:53248
	ds_read_b128 v[224:227], v191 offset:54272
	ds_read_b128 v[238:241], v191 offset:55296
	ds_read_b128 v[242:245], v191 offset:56320
	global_load_lds_dwordx4 v[166:167], off
	s_add_i32 m0, s4, 0x2000
	s_add_u32 s4, s56, 0x40080
	v_lshl_add_u64 v[166:167], v[170:171], 0, s[42:43]
	s_addc_u32 s5, s57, 0
	s_add_i32 s6, s7, s70
	global_load_lds_dwordx4 v[166:167], off
	v_lshl_add_u64 v[166:167], s[4:5], 0, v[148:149]
	s_mov_b32 m0, s6
	s_nop 0
	global_load_lds_dwordx4 v[166:167], off
	v_lshl_add_u64 v[166:167], s[4:5], 0, v[152:153]
	s_add_i32 m0, s6, 0x2000
	s_nop 0
	global_load_lds_dwordx4 v[166:167], off
	v_lshl_add_u64 v[166:167], v[176:177], 0, s[42:43]
	s_add_i32 m0, s44, 0x8000
	s_nop 0
	global_load_lds_dwordx4 v[166:167], off
	v_lshl_add_u64 v[166:167], v[180:181], 0, s[42:43]
	s_add_i32 m0, s44, 0xa000
	s_nop 0
	global_load_lds_dwordx4 v[166:167], off
	s_waitcnt vmcnt(8)
	s_waitcnt lgkmcnt(0)
	s_setprio 1
	s_barrier
	v_mfma_f32_16x16x32_bf16 v[62:65], v[132:135], v[204:207], v[62:65]
	v_mfma_f32_16x16x32_bf16 v[58:61], v[140:143], v[204:207], v[58:61]
	v_mfma_f32_16x16x32_bf16 v[46:49], v[132:135], v[212:215], v[46:49]
	v_mfma_f32_16x16x32_bf16 v[42:45], v[140:143], v[212:215], v[42:45]
	v_mfma_f32_16x16x32_bf16 v[30:33], v[132:135], v[220:223], v[30:33]
	v_mfma_f32_16x16x32_bf16 v[26:29], v[140:143], v[220:223], v[26:29]
	v_mfma_f32_16x16x32_bf16 v[14:17], v[132:135], v[238:241], v[14:17]
	v_mfma_f32_16x16x32_bf16 v[10:13], v[140:143], v[238:241], v[10:13]
	v_mfma_f32_16x16x32_bf16 v[62:65], v[136:139], v[208:211], v[62:65]
	v_mfma_f32_16x16x32_bf16 v[58:61], v[144:147], v[208:211], v[58:61]
	v_mfma_f32_16x16x32_bf16 v[46:49], v[136:139], v[216:219], v[46:49]
	v_mfma_f32_16x16x32_bf16 v[42:45], v[144:147], v[216:219], v[42:45]
	v_mfma_f32_16x16x32_bf16 v[30:33], v[136:139], v[224:227], v[30:33]
	v_mfma_f32_16x16x32_bf16 v[26:29], v[144:147], v[224:227], v[26:29]
	v_mfma_f32_16x16x32_bf16 v[14:17], v[136:139], v[242:245], v[14:17]
	v_mfma_f32_16x16x32_bf16 v[10:13], v[144:147], v[242:245], v[10:13]
	s_setprio 0
	s_setprio 1
	v_mfma_f32_16x16x32_bf16 v[54:57], v[156:159], v[204:207], v[54:57]
	v_mfma_f32_16x16x32_bf16 v[50:53], v[192:195], v[204:207], v[50:53]
	v_mfma_f32_16x16x32_bf16 v[38:41], v[156:159], v[212:215], v[38:41]
	v_mfma_f32_16x16x32_bf16 v[34:37], v[192:195], v[212:215], v[34:37]
	v_mfma_f32_16x16x32_bf16 v[22:25], v[156:159], v[220:223], v[22:25]
	v_mfma_f32_16x16x32_bf16 v[18:21], v[192:195], v[220:223], v[18:21]
	v_mfma_f32_16x16x32_bf16 v[6:9], v[156:159], v[238:241], v[6:9]
	v_mfma_f32_16x16x32_bf16 v[2:5], v[192:195], v[238:241], v[2:5]
	v_mfma_f32_16x16x32_bf16 v[54:57], v[162:165], v[208:211], v[54:57]
	v_mfma_f32_16x16x32_bf16 v[50:53], v[200:203], v[208:211], v[50:53]
	v_mfma_f32_16x16x32_bf16 v[38:41], v[162:165], v[216:219], v[38:41]
	v_mfma_f32_16x16x32_bf16 v[34:37], v[200:203], v[216:219], v[34:37]
	v_mfma_f32_16x16x32_bf16 v[22:25], v[162:165], v[224:227], v[22:25]
	v_mfma_f32_16x16x32_bf16 v[18:21], v[200:203], v[224:227], v[18:21]
	v_mfma_f32_16x16x32_bf16 v[6:9], v[162:165], v[242:245], v[6:9]
	v_mfma_f32_16x16x32_bf16 v[2:5], v[200:203], v[242:245], v[2:5]
	s_setprio 0
	s_barrier
	s_mov_b32 s100, 0
	s_add_i32 s92, s92, 2
	s_add_u32 s40, s40, 0x100
	s_addc_u32 s41, s41, 0
	s_add_u32 s90, s90, 0x100
	s_addc_u32 s91, s91, 0
	s_cmp_gt_u32 s92, 13
	s_cbranch_scc0 .LBB0_1011
	s_mov_b32 s100, 1
	s_and_b64 vcc, exec, s[0:1]
	s_cbranch_vccz .LBB0_1014
	s_barrier

.Lmy_sk9:
	s_waitcnt lgkmcnt(0)
	s_setprio 1
	s_barrier
	v_mfma_f32_16x16x32_bf16 v[144:147], v[112:115], v[164:167], v[144:147]
	v_mfma_f32_16x16x32_bf16 v[140:143], v[124:127], v[164:167], v[140:143]
	v_mfma_f32_16x16x32_bf16 v[120:123], v[112:115], v[178:181], v[120:123]
	v_mfma_f32_16x16x32_bf16 v[108:111], v[124:127], v[178:181], v[108:111]
	v_mfma_f32_16x16x32_bf16 v[94:97], v[112:115], v[186:189], v[94:97]
	v_mfma_f32_16x16x32_bf16 v[90:93], v[124:127], v[186:189], v[90:93]
	v_mfma_f32_16x16x32_bf16 v[78:81], v[112:115], v[200:203], v[78:81]
	v_mfma_f32_16x16x32_bf16 v[74:77], v[124:127], v[200:203], v[74:77]
	v_mfma_f32_16x16x32_bf16 v[144:147], v[116:119], v[168:171], v[144:147]
	v_mfma_f32_16x16x32_bf16 v[140:143], v[128:131], v[168:171], v[140:143]
	v_mfma_f32_16x16x32_bf16 v[120:123], v[116:119], v[182:185], v[120:123]
	v_mfma_f32_16x16x32_bf16 v[108:111], v[128:131], v[182:185], v[108:111]
	v_mfma_f32_16x16x32_bf16 v[94:97], v[116:119], v[190:193], v[94:97]
	v_mfma_f32_16x16x32_bf16 v[90:93], v[128:131], v[190:193], v[90:93]
	v_mfma_f32_16x16x32_bf16 v[78:81], v[116:119], v[208:211], v[78:81]
	v_mfma_f32_16x16x32_bf16 v[74:77], v[128:131], v[208:211], v[74:77]
	s_setprio 0
	s_setprio 1
	v_mfma_f32_16x16x32_bf16 v[136:139], v[148:151], v[164:167], v[136:139]
	v_mfma_f32_16x16x32_bf16 v[132:135], v[156:159], v[164:167], v[132:135]
	v_mfma_f32_16x16x32_bf16 v[104:107], v[148:151], v[178:181], v[104:107]
	v_mfma_f32_16x16x32_bf16 v[100:103], v[156:159], v[178:181], v[100:103]
	v_mfma_f32_16x16x32_bf16 v[86:89], v[148:151], v[186:189], v[86:89]
	v_mfma_f32_16x16x32_bf16 v[82:85], v[156:159], v[186:189], v[82:85]
	v_mfma_f32_16x16x32_bf16 v[70:73], v[148:151], v[200:203], v[70:73]
	v_mfma_f32_16x16x32_bf16 v[66:69], v[156:159], v[200:203], v[66:69]
	v_mfma_f32_16x16x32_bf16 v[136:139], v[152:155], v[168:171], v[136:139]
	v_mfma_f32_16x16x32_bf16 v[132:135], v[160:163], v[168:171], v[132:135]
	v_mfma_f32_16x16x32_bf16 v[104:107], v[152:155], v[182:185], v[104:107]
	v_mfma_f32_16x16x32_bf16 v[100:103], v[160:163], v[182:185], v[100:103]
	v_mfma_f32_16x16x32_bf16 v[86:89], v[152:155], v[190:193], v[86:89]
	v_mfma_f32_16x16x32_bf16 v[82:85], v[160:163], v[190:193], v[82:85]
	v_mfma_f32_16x16x32_bf16 v[70:73], v[152:155], v[208:211], v[70:73]
	v_mfma_f32_16x16x32_bf16 v[66:69], v[160:163], v[208:211], v[66:69]
	s_setprio 0
	s_barrier
	s_add_i32 s4, s6, s91
	v_lshl_add_u64 v[194:195], s[78:79], 0, v[172:173]
	s_mov_b32 m0, s4
	ds_read_b128 v[164:167], v207 offset:16384
	ds_read_b128 v[168:171], v207 offset:17408
	ds_read_b128 v[178:181], v207 offset:18432
	ds_read_b128 v[182:185], v207 offset:19456
	ds_read_b128 v[186:189], v207 offset:20480
	ds_read_b128 v[190:193], v207 offset:21504
	ds_read_b128 v[200:203], v207 offset:22528
	ds_read_b128 v[208:211], v207 offset:23552
	global_load_lds_dwordx4 v[194:195], off
	s_add_i32 m0, s4, 0x2000
	s_add_u32 s4, s78, 0x100000
	v_lshl_add_u64 v[212:213], s[78:79], 0, v[176:177]
	s_addc_u32 s5, s79, 0
	s_add_i32 s6, s7, s91
	global_load_lds_dwordx4 v[212:213], off
	v_lshl_add_u64 v[214:215], s[4:5], 0, v[172:173]
	s_mov_b32 m0, s6
	v_lshl_add_u64 v[216:217], vcc, 0, v[174:175]
	global_load_lds_dwordx4 v[214:215], off
	v_lshl_add_u64 v[214:215], s[4:5], 0, v[176:177]
	s_add_i32 m0, s6, 0x2000
	s_nop 0
	global_load_lds_dwordx4 v[214:215], off
	v_lshl_add_u64 v[214:215], vcc, 0, v[98:99]
	s_mov_b32 m0, s44
	s_nop 0
	global_load_lds_dwordx4 v[214:215], off
	s_add_i32 m0, s44, 0x2000
	s_nop 0
	global_load_lds_dwordx4 v[216:217], off
	s_cmp_eq_u32 s100, 1
	s_cbranch_scc1 .Lmy_sk10
	s_waitcnt vmcnt(8)
.Lmy_sk10:
	s_waitcnt lgkmcnt(0)
	s_setprio 1
	s_barrier
	v_mfma_f32_16x16x32_bf16 v[62:65], v[112:115], v[164:167], v[62:65]
	v_mfma_f32_16x16x32_bf16 v[58:61], v[124:127], v[164:167], v[58:61]
	v_mfma_f32_16x16x32_bf16 v[46:49], v[112:115], v[178:181], v[46:49]
	v_mfma_f32_16x16x32_bf16 v[42:45], v[124:127], v[178:181], v[42:45]
	v_mfma_f32_16x16x32_bf16 v[30:33], v[112:115], v[186:189], v[30:33]
	v_mfma_f32_16x16x32_bf16 v[26:29], v[124:127], v[186:189], v[26:29]
	v_mfma_f32_16x16x32_bf16 v[14:17], v[112:115], v[200:203], v[14:17]
	v_mfma_f32_16x16x32_bf16 v[10:13], v[124:127], v[200:203], v[10:13]
	v_mfma_f32_16x16x32_bf16 v[62:65], v[116:119], v[168:171], v[62:65]
	v_mfma_f32_16x16x32_bf16 v[58:61], v[128:131], v[168:171], v[58:61]
	v_mfma_f32_16x16x32_bf16 v[46:49], v[116:119], v[182:185], v[46:49]
	v_mfma_f32_16x16x32_bf16 v[42:45], v[128:131], v[182:185], v[42:45]
	v_mfma_f32_16x16x32_bf16 v[30:33], v[116:119], v[190:193], v[30:33]
	v_mfma_f32_16x16x32_bf16 v[26:29], v[128:131], v[190:193], v[26:29]
	v_mfma_f32_16x16x32_bf16 v[14:17], v[116:119], v[208:211], v[14:17]
	v_mfma_f32_16x16x32_bf16 v[10:13], v[128:131], v[208:211], v[10:13]
	s_setprio 0
	s_setprio 1
	v_mfma_f32_16x16x32_bf16 v[54:57], v[148:151], v[164:167], v[54:57]
	v_mfma_f32_16x16x32_bf16 v[50:53], v[156:159], v[164:167], v[50:53]
	v_mfma_f32_16x16x32_bf16 v[38:41], v[148:151], v[178:181], v[38:41]
	v_mfma_f32_16x16x32_bf16 v[34:37], v[156:159], v[178:181], v[34:37]
	v_mfma_f32_16x16x32_bf16 v[22:25], v[148:151], v[186:189], v[22:25]
	v_mfma_f32_16x16x32_bf16 v[18:21], v[156:159], v[186:189], v[18:21]
	v_mfma_f32_16x16x32_bf16 v[6:9], v[148:151], v[200:203], v[6:9]
	v_mfma_f32_16x16x32_bf16 v[2:5], v[156:159], v[200:203], v[2:5]
	v_mfma_f32_16x16x32_bf16 v[54:57], v[152:155], v[168:171], v[54:57]
	v_mfma_f32_16x16x32_bf16 v[50:53], v[160:163], v[168:171], v[50:53]
	v_mfma_f32_16x16x32_bf16 v[38:41], v[152:155], v[182:185], v[38:41]
	v_mfma_f32_16x16x32_bf16 v[34:37], v[160:163], v[182:185], v[34:37]
	v_mfma_f32_16x16x32_bf16 v[22:25], v[152:155], v[190:193], v[22:25]
	v_mfma_f32_16x16x32_bf16 v[18:21], v[160:163], v[190:193], v[18:21]
	v_mfma_f32_16x16x32_bf16 v[6:9], v[152:155], v[208:211], v[6:9]
	v_mfma_f32_16x16x32_bf16 v[2:5], v[160:163], v[208:211], v[2:5]
	s_setprio 0
	s_barrier
	s_add_i32 s6, 0, 0x18000
	s_add_i32 s7, 0, 0x1c000
	v_add_u32_e32 v128, s6, v205
	v_add_u32_e32 v160, s7, v205
	ds_read_b128 v[112:115], v128
	ds_read_b128 v[116:119], v128 offset:1024
	ds_read_b128 v[124:127], v128 offset:2048
	ds_read_b128 v[128:131], v128 offset:3072
	ds_read_b128 v[148:151], v160
	ds_read_b128 v[152:155], v160 offset:1024
	ds_read_b128 v[156:159], v160 offset:2048
	ds_read_b128 v[160:163], v160 offset:3072
	s_add_u32 s4, vcc_lo, 0x100000
	s_addc_u32 s5, vcc_hi, 0
	v_lshl_add_u64 v[218:219], s[4:5], 0, v[98:99]
	s_add_i32 m0, s44, 0x4000
	ds_read_b128 v[164:167], v207 offset:32768
	ds_read_b128 v[168:171], v207 offset:33792
	ds_read_b128 v[178:181], v207 offset:34816
	ds_read_b128 v[182:185], v207 offset:35840
	ds_read_b128 v[186:189], v207 offset:36864
	ds_read_b128 v[190:193], v207 offset:37888
	ds_read_b128 v[200:203], v207 offset:38912
	ds_read_b128 v[208:211], v207 offset:39936
	global_load_lds_dwordx4 v[218:219], off
	v_lshl_add_u64 v[218:219], s[4:5], 0, v[174:175]
	s_add_i32 m0, s44, 0x6000
	s_nop 0
	global_load_lds_dwordx4 v[218:219], off
	s_waitcnt vmcnt(8)
	s_waitcnt lgkmcnt(0)
	s_setprio 1
	s_barrier
	v_mfma_f32_16x16x32_bf16 v[144:147], v[112:115], v[164:167], v[144:147]
	v_mfma_f32_16x16x32_bf16 v[140:143], v[124:127], v[164:167], v[140:143]
	v_mfma_f32_16x16x32_bf16 v[120:123], v[112:115], v[178:181], v[120:123]
	v_mfma_f32_16x16x32_bf16 v[108:111], v[124:127], v[178:181], v[108:111]
	v_mfma_f32_16x16x32_bf16 v[94:97], v[112:115], v[186:189], v[94:97]
	v_mfma_f32_16x16x32_bf16 v[90:93], v[124:127], v[186:189], v[90:93]
	v_mfma_f32_16x16x32_bf16 v[78:81], v[112:115], v[200:203], v[78:81]
	v_mfma_f32_16x16x32_bf16 v[74:77], v[124:127], v[200:203], v[74:77]
	v_mfma_f32_16x16x32_bf16 v[144:147], v[116:119], v[168:171], v[144:147]
	v_mfma_f32_16x16x32_bf16 v[140:143], v[128:131], v[168:171], v[140:143]
	v_mfma_f32_16x16x32_bf16 v[120:123], v[116:119], v[182:185], v[120:123]
	v_mfma_f32_16x16x32_bf16 v[108:111], v[128:131], v[182:185], v[108:111]
	v_mfma_f32_16x16x32_bf16 v[94:97], v[116:119], v[190:193], v[94:97]
	v_mfma_f32_16x16x32_bf16 v[90:93], v[128:131], v[190:193], v[90:93]
	v_mfma_f32_16x16x32_bf16 v[78:81], v[116:119], v[208:211], v[78:81]
	v_mfma_f32_16x16x32_bf16 v[74:77], v[128:131], v[208:211], v[74:77]
	s_setprio 0
	s_setprio 1
	v_mfma_f32_16x16x32_bf16 v[136:139], v[148:151], v[164:167], v[136:139]
	v_mfma_f32_16x16x32_bf16 v[132:135], v[156:159], v[164:167], v[132:135]
	v_mfma_f32_16x16x32_bf16 v[104:107], v[148:151], v[178:181], v[104:107]
	v_mfma_f32_16x16x32_bf16 v[100:103], v[156:159], v[178:181], v[100:103]
	v_mfma_f32_16x16x32_bf16 v[86:89], v[148:151], v[186:189], v[86:89]
	v_mfma_f32_16x16x32_bf16 v[82:85], v[156:159], v[186:189], v[82:85]
	v_mfma_f32_16x16x32_bf16 v[70:73], v[148:151], v[200:203], v[70:73]
	v_mfma_f32_16x16x32_bf16 v[66:69], v[156:159], v[200:203], v[66:69]
	v_mfma_f32_16x16x32_bf16 v[136:139], v[152:155], v[168:171], v[136:139]
	v_mfma_f32_16x16x32_bf16 v[132:135], v[160:163], v[168:171], v[132:135]
	v_mfma_f32_16x16x32_bf16 v[104:107], v[152:155], v[182:185], v[104:107]
	v_mfma_f32_16x16x32_bf16 v[100:103], v[160:163], v[182:185], v[100:103]
	v_mfma_f32_16x16x32_bf16 v[86:89], v[152:155], v[190:193], v[86:89]
	v_mfma_f32_16x16x32_bf16 v[82:85], v[160:163], v[190:193], v[82:85]
	v_mfma_f32_16x16x32_bf16 v[70:73], v[152:155], v[208:211], v[70:73]
	v_mfma_f32_16x16x32_bf16 v[66:69], v[160:163], v[208:211], v[66:69]
	s_setprio 0
	s_barrier
	s_add_i32 s4, s6, s91
	v_lshl_add_u64 v[194:195], v[194:195], 0, s[42:43]
	s_mov_b32 m0, s4
	ds_read_b128 v[164:167], v207 offset:49152
	ds_read_b128 v[168:171], v207 offset:50176
	ds_read_b128 v[178:181], v207 offset:51200
	ds_read_b128 v[182:185], v207 offset:52224
	ds_read_b128 v[186:189], v207 offset:53248
	ds_read_b128 v[190:193], v207 offset:54272
	ds_read_b128 v[200:203], v207 offset:55296
	ds_read_b128 v[208:211], v207 offset:56320
	global_load_lds_dwordx4 v[194:195], off
	s_add_i32 m0, s4, 0x2000
	s_add_u32 s4, s78, 0x100080
	v_lshl_add_u64 v[194:195], v[212:213], 0, s[42:43]
	s_addc_u32 s5, s79, 0
	s_add_i32 s6, s7, s91
	global_load_lds_dwordx4 v[194:195], off
	v_lshl_add_u64 v[194:195], s[4:5], 0, v[172:173]
	s_mov_b32 m0, s6
	s_nop 0
	global_load_lds_dwordx4 v[194:195], off
	v_lshl_add_u64 v[194:195], s[4:5], 0, v[176:177]
	s_add_i32 m0, s6, 0x2000
	s_nop 0
	global_load_lds_dwordx4 v[194:195], off
	v_lshl_add_u64 v[194:195], v[214:215], 0, s[42:43]
	s_add_i32 m0, s44, 0x8000
	s_nop 0
	global_load_lds_dwordx4 v[194:195], off
	v_lshl_add_u64 v[194:195], v[216:217], 0, s[42:43]
	s_add_i32 m0, s44, 0xa000
	s_nop 0
	global_load_lds_dwordx4 v[194:195], off
	s_waitcnt vmcnt(8)
	s_waitcnt lgkmcnt(0)
	s_setprio 1
	s_barrier
	v_mfma_f32_16x16x32_bf16 v[62:65], v[112:115], v[164:167], v[62:65]
	v_mfma_f32_16x16x32_bf16 v[58:61], v[124:127], v[164:167], v[58:61]
	v_mfma_f32_16x16x32_bf16 v[46:49], v[112:115], v[178:181], v[46:49]
	v_mfma_f32_16x16x32_bf16 v[42:45], v[124:127], v[178:181], v[42:45]
	v_mfma_f32_16x16x32_bf16 v[30:33], v[112:115], v[186:189], v[30:33]
	v_mfma_f32_16x16x32_bf16 v[26:29], v[124:127], v[186:189], v[26:29]
	v_mfma_f32_16x16x32_bf16 v[14:17], v[112:115], v[200:203], v[14:17]
	v_mfma_f32_16x16x32_bf16 v[10:13], v[124:127], v[200:203], v[10:13]
	v_mfma_f32_16x16x32_bf16 v[62:65], v[116:119], v[168:171], v[62:65]
	v_mfma_f32_16x16x32_bf16 v[58:61], v[128:131], v[168:171], v[58:61]
	v_mfma_f32_16x16x32_bf16 v[46:49], v[116:119], v[182:185], v[46:49]
	v_mfma_f32_16x16x32_bf16 v[42:45], v[128:131], v[182:185], v[42:45]
	v_mfma_f32_16x16x32_bf16 v[30:33], v[116:119], v[190:193], v[30:33]
	v_mfma_f32_16x16x32_bf16 v[26:29], v[128:131], v[190:193], v[26:29]
	v_mfma_f32_16x16x32_bf16 v[14:17], v[116:119], v[208:211], v[14:17]
	v_mfma_f32_16x16x32_bf16 v[10:13], v[128:131], v[208:211], v[10:13]
	s_setprio 0
	s_setprio 1
	v_mfma_f32_16x16x32_bf16 v[54:57], v[148:151], v[164:167], v[54:57]
	v_mfma_f32_16x16x32_bf16 v[50:53], v[156:159], v[164:167], v[50:53]
	v_mfma_f32_16x16x32_bf16 v[38:41], v[148:151], v[178:181], v[38:41]
	v_mfma_f32_16x16x32_bf16 v[34:37], v[156:159], v[178:181], v[34:37]
	v_mfma_f32_16x16x32_bf16 v[22:25], v[148:151], v[186:189], v[22:25]
	v_mfma_f32_16x16x32_bf16 v[18:21], v[156:159], v[186:189], v[18:21]
	v_mfma_f32_16x16x32_bf16 v[6:9], v[148:151], v[200:203], v[6:9]
	v_mfma_f32_16x16x32_bf16 v[2:5], v[156:159], v[200:203], v[2:5]
	v_mfma_f32_16x16x32_bf16 v[54:57], v[152:155], v[168:171], v[54:57]
	v_mfma_f32_16x16x32_bf16 v[50:53], v[160:163], v[168:171], v[50:53]
	v_mfma_f32_16x16x32_bf16 v[38:41], v[152:155], v[182:185], v[38:41]
	v_mfma_f32_16x16x32_bf16 v[34:37], v[160:163], v[182:185], v[34:37]
	v_mfma_f32_16x16x32_bf16 v[22:25], v[152:155], v[190:193], v[22:25]
	v_mfma_f32_16x16x32_bf16 v[18:21], v[160:163], v[190:193], v[18:21]
	v_mfma_f32_16x16x32_bf16 v[6:9], v[152:155], v[208:211], v[6:9]
	v_mfma_f32_16x16x32_bf16 v[2:5], v[160:163], v[208:211], v[2:5]
	s_setprio 0
	s_barrier
	s_mov_b32 s100, 0
	s_add_i32 s95, s95, 2
	s_add_u32 s74, s74, 0x100
	s_addc_u32 s75, s75, 0
	s_add_u32 s71, s71, 0x100
	s_addc_u32 s94, s94, 0
	s_cmp_gt_u32 s95, 61
	s_cbranch_scc0 .LBB0_1116
	s_mov_b32 s100, 1
	s_and_b64 vcc, exec, s[10:11]
	s_cbranch_vccz .LBB0_1119
	s_barrier

.Lmy_sk11:
	s_waitcnt lgkmcnt(0)
	s_setprio 1
	s_barrier
	v_mfma_f32_16x16x32_bf16 v[160:163], v[90:93], v[164:167], v[160:163]
	v_mfma_f32_16x16x32_bf16 v[156:159], v[100:103], v[164:167], v[156:159]
	v_mfma_f32_16x16x32_bf16 v[144:147], v[90:93], v[172:175], v[144:147]
	v_mfma_f32_16x16x32_bf16 v[140:143], v[100:103], v[172:175], v[140:143]
	v_mfma_f32_16x16x32_bf16 v[124:127], v[90:93], v[180:183], v[124:127]
	v_mfma_f32_16x16x32_bf16 v[116:119], v[100:103], v[180:183], v[116:119]
	v_mfma_f32_16x16x32_bf16 v[78:81], v[90:93], v[188:191], v[78:81]
	v_mfma_f32_16x16x32_bf16 v[74:77], v[100:103], v[188:191], v[74:77]
	v_mfma_f32_16x16x32_bf16 v[160:163], v[94:97], v[168:171], v[160:163]
	v_mfma_f32_16x16x32_bf16 v[156:159], v[104:107], v[168:171], v[156:159]
	v_mfma_f32_16x16x32_bf16 v[144:147], v[94:97], v[176:179], v[144:147]
	v_mfma_f32_16x16x32_bf16 v[140:143], v[104:107], v[176:179], v[140:143]
	v_mfma_f32_16x16x32_bf16 v[124:127], v[94:97], v[184:187], v[124:127]
	v_mfma_f32_16x16x32_bf16 v[116:119], v[104:107], v[184:187], v[116:119]
	v_mfma_f32_16x16x32_bf16 v[78:81], v[94:97], v[192:195], v[78:81]
	v_mfma_f32_16x16x32_bf16 v[74:77], v[104:107], v[192:195], v[74:77]
	s_setprio 0
	s_setprio 1
	v_mfma_f32_16x16x32_bf16 v[152:155], v[108:111], v[164:167], v[152:155]
	v_mfma_f32_16x16x32_bf16 v[148:151], v[120:123], v[164:167], v[148:151]
	v_mfma_f32_16x16x32_bf16 v[136:139], v[108:111], v[172:175], v[136:139]
	v_mfma_f32_16x16x32_bf16 v[132:135], v[120:123], v[172:175], v[132:135]
	v_mfma_f32_16x16x32_bf16 v[86:89], v[108:111], v[180:183], v[86:89]
	v_mfma_f32_16x16x32_bf16 v[82:85], v[120:123], v[180:183], v[82:85]
	v_mfma_f32_16x16x32_bf16 v[70:73], v[108:111], v[188:191], v[70:73]
	v_mfma_f32_16x16x32_bf16 v[66:69], v[120:123], v[188:191], v[66:69]
	v_mfma_f32_16x16x32_bf16 v[152:155], v[112:115], v[168:171], v[152:155]
	v_mfma_f32_16x16x32_bf16 v[148:151], v[128:131], v[168:171], v[148:151]
	v_mfma_f32_16x16x32_bf16 v[136:139], v[112:115], v[176:179], v[136:139]
	v_mfma_f32_16x16x32_bf16 v[132:135], v[128:131], v[176:179], v[132:135]
	v_mfma_f32_16x16x32_bf16 v[86:89], v[112:115], v[184:187], v[86:89]
	v_mfma_f32_16x16x32_bf16 v[82:85], v[128:131], v[184:187], v[82:85]
	v_mfma_f32_16x16x32_bf16 v[70:73], v[112:115], v[192:195], v[70:73]
	v_mfma_f32_16x16x32_bf16 v[66:69], v[128:131], v[192:195], v[66:69]
	s_setprio 0
	s_barrier
	s_add_i32 s4, s6, s91
	v_lshl_add_u64 v[200:201], s[74:75], 0, v[204:205]
	s_mov_b32 m0, s4
	ds_read_b128 v[164:167], v241 offset:16384
	ds_read_b128 v[168:171], v241 offset:17408
	ds_read_b128 v[172:175], v241 offset:18432
	ds_read_b128 v[176:179], v241 offset:19456
	ds_read_b128 v[180:183], v241 offset:20480
	ds_read_b128 v[184:187], v241 offset:21504
	ds_read_b128 v[188:191], v241 offset:22528
	ds_read_b128 v[192:195], v241 offset:23552
	global_load_lds_dwordx4 v[200:201], off
	s_add_i32 m0, s4, 0x2000
	s_add_u32 s4, s74, 0x100000
	v_lshl_add_u64 v[202:203], s[74:75], 0, v[208:209]
	s_addc_u32 s5, s75, 0
	s_add_i32 s6, s7, s91
	global_load_lds_dwordx4 v[202:203], off
	v_lshl_add_u64 v[210:211], s[4:5], 0, v[204:205]
	s_mov_b32 m0, s6
	v_lshl_add_u64 v[212:213], s[78:79], 0, v[206:207]
	global_load_lds_dwordx4 v[210:211], off
	v_lshl_add_u64 v[210:211], s[4:5], 0, v[208:209]
	s_add_i32 m0, s6, 0x2000
	s_nop 0
	global_load_lds_dwordx4 v[210:211], off
	v_lshl_add_u64 v[210:211], s[78:79], 0, v[98:99]
	s_mov_b32 m0, s44
	s_nop 0
	global_load_lds_dwordx4 v[210:211], off
	s_add_i32 m0, s44, 0x2000
	s_nop 0
	global_load_lds_dwordx4 v[212:213], off
	s_cmp_eq_u32 s100, 1
	s_cbranch_scc1 .Lmy_sk12
	s_waitcnt vmcnt(8)
.Lmy_sk12:
	s_waitcnt lgkmcnt(0)
	s_setprio 1
	s_barrier
	v_mfma_f32_16x16x32_bf16 v[62:65], v[90:93], v[164:167], v[62:65]
	v_mfma_f32_16x16x32_bf16 v[58:61], v[100:103], v[164:167], v[58:61]
	v_mfma_f32_16x16x32_bf16 v[46:49], v[90:93], v[172:175], v[46:49]
	v_mfma_f32_16x16x32_bf16 v[42:45], v[100:103], v[172:175], v[42:45]
	v_mfma_f32_16x16x32_bf16 v[30:33], v[90:93], v[180:183], v[30:33]
	v_mfma_f32_16x16x32_bf16 v[26:29], v[100:103], v[180:183], v[26:29]
	v_mfma_f32_16x16x32_bf16 v[14:17], v[90:93], v[188:191], v[14:17]
	v_mfma_f32_16x16x32_bf16 v[10:13], v[100:103], v[188:191], v[10:13]
	v_mfma_f32_16x16x32_bf16 v[62:65], v[94:97], v[168:171], v[62:65]
	v_mfma_f32_16x16x32_bf16 v[58:61], v[104:107], v[168:171], v[58:61]
	v_mfma_f32_16x16x32_bf16 v[46:49], v[94:97], v[176:179], v[46:49]
	v_mfma_f32_16x16x32_bf16 v[42:45], v[104:107], v[176:179], v[42:45]
	v_mfma_f32_16x16x32_bf16 v[30:33], v[94:97], v[184:187], v[30:33]
	v_mfma_f32_16x16x32_bf16 v[26:29], v[104:107], v[184:187], v[26:29]
	v_mfma_f32_16x16x32_bf16 v[14:17], v[94:97], v[192:195], v[14:17]
	v_mfma_f32_16x16x32_bf16 v[10:13], v[104:107], v[192:195], v[10:13]
	s_setprio 0
	s_setprio 1
	v_mfma_f32_16x16x32_bf16 v[54:57], v[108:111], v[164:167], v[54:57]
	v_mfma_f32_16x16x32_bf16 v[50:53], v[120:123], v[164:167], v[50:53]
	v_mfma_f32_16x16x32_bf16 v[38:41], v[108:111], v[172:175], v[38:41]
	v_mfma_f32_16x16x32_bf16 v[34:37], v[120:123], v[172:175], v[34:37]
	v_mfma_f32_16x16x32_bf16 v[22:25], v[108:111], v[180:183], v[22:25]
	v_mfma_f32_16x16x32_bf16 v[18:21], v[120:123], v[180:183], v[18:21]
	v_mfma_f32_16x16x32_bf16 v[6:9], v[108:111], v[188:191], v[6:9]
	v_mfma_f32_16x16x32_bf16 v[2:5], v[120:123], v[188:191], v[2:5]
	v_mfma_f32_16x16x32_bf16 v[54:57], v[112:115], v[168:171], v[54:57]
	v_mfma_f32_16x16x32_bf16 v[50:53], v[128:131], v[168:171], v[50:53]
	v_mfma_f32_16x16x32_bf16 v[38:41], v[112:115], v[176:179], v[38:41]
	v_mfma_f32_16x16x32_bf16 v[34:37], v[128:131], v[176:179], v[34:37]
	v_mfma_f32_16x16x32_bf16 v[22:25], v[112:115], v[184:187], v[22:25]
	v_mfma_f32_16x16x32_bf16 v[18:21], v[128:131], v[184:187], v[18:21]
	v_mfma_f32_16x16x32_bf16 v[6:9], v[112:115], v[192:195], v[6:9]
	v_mfma_f32_16x16x32_bf16 v[2:5], v[128:131], v[192:195], v[2:5]
	s_setprio 0
	s_barrier
	s_add_i32 s6, 0, 0x18000
	s_add_i32 s7, 0, 0x1c000
	v_add_u32_e32 v104, s6, v239
	v_add_u32_e32 v128, s7, v239
	ds_read_b128 v[90:93], v104
	ds_read_b128 v[94:97], v104 offset:1024
	ds_read_b128 v[100:103], v104 offset:2048
	ds_read_b128 v[104:107], v104 offset:3072
	ds_read_b128 v[108:111], v128
	ds_read_b128 v[112:115], v128 offset:1024
	ds_read_b128 v[120:123], v128 offset:2048
	ds_read_b128 v[128:131], v128 offset:3072
	s_add_u32 s4, s78, 0x100000
	s_addc_u32 s5, s79, 0
	v_lshl_add_u64 v[214:215], s[4:5], 0, v[98:99]
	s_add_i32 m0, s44, 0x4000
	ds_read_b128 v[164:167], v241 offset:32768
	ds_read_b128 v[168:171], v241 offset:33792
	ds_read_b128 v[172:175], v241 offset:34816
	ds_read_b128 v[176:179], v241 offset:35840
	ds_read_b128 v[180:183], v241 offset:36864
	ds_read_b128 v[184:187], v241 offset:37888
	ds_read_b128 v[188:191], v241 offset:38912
	ds_read_b128 v[192:195], v241 offset:39936
	global_load_lds_dwordx4 v[214:215], off
	v_lshl_add_u64 v[214:215], s[4:5], 0, v[206:207]
	s_add_i32 m0, s44, 0x6000
	s_nop 0
	global_load_lds_dwordx4 v[214:215], off
	s_waitcnt vmcnt(8)
	s_waitcnt lgkmcnt(0)
	s_setprio 1
	s_barrier
	v_mfma_f32_16x16x32_bf16 v[160:163], v[90:93], v[164:167], v[160:163]
	v_mfma_f32_16x16x32_bf16 v[156:159], v[100:103], v[164:167], v[156:159]
	v_mfma_f32_16x16x32_bf16 v[144:147], v[90:93], v[172:175], v[144:147]
	v_mfma_f32_16x16x32_bf16 v[140:143], v[100:103], v[172:175], v[140:143]
	v_mfma_f32_16x16x32_bf16 v[124:127], v[90:93], v[180:183], v[124:127]
	v_mfma_f32_16x16x32_bf16 v[116:119], v[100:103], v[180:183], v[116:119]
	v_mfma_f32_16x16x32_bf16 v[78:81], v[90:93], v[188:191], v[78:81]
	v_mfma_f32_16x16x32_bf16 v[74:77], v[100:103], v[188:191], v[74:77]
	v_mfma_f32_16x16x32_bf16 v[160:163], v[94:97], v[168:171], v[160:163]
	v_mfma_f32_16x16x32_bf16 v[156:159], v[104:107], v[168:171], v[156:159]
	v_mfma_f32_16x16x32_bf16 v[144:147], v[94:97], v[176:179], v[144:147]
	v_mfma_f32_16x16x32_bf16 v[140:143], v[104:107], v[176:179], v[140:143]
	v_mfma_f32_16x16x32_bf16 v[124:127], v[94:97], v[184:187], v[124:127]
	v_mfma_f32_16x16x32_bf16 v[116:119], v[104:107], v[184:187], v[116:119]
	v_mfma_f32_16x16x32_bf16 v[78:81], v[94:97], v[192:195], v[78:81]
	v_mfma_f32_16x16x32_bf16 v[74:77], v[104:107], v[192:195], v[74:77]
	s_setprio 0
	s_setprio 1
	v_mfma_f32_16x16x32_bf16 v[152:155], v[108:111], v[164:167], v[152:155]
	v_mfma_f32_16x16x32_bf16 v[148:151], v[120:123], v[164:167], v[148:151]
	v_mfma_f32_16x16x32_bf16 v[136:139], v[108:111], v[172:175], v[136:139]
	v_mfma_f32_16x16x32_bf16 v[132:135], v[120:123], v[172:175], v[132:135]
	v_mfma_f32_16x16x32_bf16 v[86:89], v[108:111], v[180:183], v[86:89]
	v_mfma_f32_16x16x32_bf16 v[82:85], v[120:123], v[180:183], v[82:85]
	v_mfma_f32_16x16x32_bf16 v[70:73], v[108:111], v[188:191], v[70:73]
	v_mfma_f32_16x16x32_bf16 v[66:69], v[120:123], v[188:191], v[66:69]
	v_mfma_f32_16x16x32_bf16 v[152:155], v[112:115], v[168:171], v[152:155]
	v_mfma_f32_16x16x32_bf16 v[148:151], v[128:131], v[168:171], v[148:151]
	v_mfma_f32_16x16x32_bf16 v[136:139], v[112:115], v[176:179], v[136:139]
	v_mfma_f32_16x16x32_bf16 v[132:135], v[128:131], v[176:179], v[132:135]
	v_mfma_f32_16x16x32_bf16 v[86:89], v[112:115], v[184:187], v[86:89]
	v_mfma_f32_16x16x32_bf16 v[82:85], v[128:131], v[184:187], v[82:85]
	v_mfma_f32_16x16x32_bf16 v[70:73], v[112:115], v[192:195], v[70:73]
	v_mfma_f32_16x16x32_bf16 v[66:69], v[128:131], v[192:195], v[66:69]
	s_setprio 0
	s_barrier
	s_add_i32 s4, s6, s91
	v_lshl_add_u64 v[200:201], v[200:201], 0, s[42:43]
	s_mov_b32 m0, s4
	ds_read_b128 v[164:167], v241 offset:49152
	ds_read_b128 v[168:171], v241 offset:50176
	ds_read_b128 v[172:175], v241 offset:51200
	ds_read_b128 v[176:179], v241 offset:52224
	ds_read_b128 v[180:183], v241 offset:53248
	ds_read_b128 v[184:187], v241 offset:54272
	ds_read_b128 v[188:191], v241 offset:55296
	ds_read_b128 v[192:195], v241 offset:56320
	global_load_lds_dwordx4 v[200:201], off
	s_add_i32 m0, s4, 0x2000
	s_add_u32 s4, s74, 0x100080
	v_lshl_add_u64 v[200:201], v[202:203], 0, s[42:43]
	s_addc_u32 s5, s75, 0
	s_add_i32 s6, s7, s91
	global_load_lds_dwordx4 v[200:201], off
	v_lshl_add_u64 v[200:201], s[4:5], 0, v[204:205]
	s_mov_b32 m0, s6
	s_nop 0
	global_load_lds_dwordx4 v[200:201], off
	v_lshl_add_u64 v[200:201], s[4:5], 0, v[208:209]
	s_add_i32 m0, s6, 0x2000
	s_nop 0
	global_load_lds_dwordx4 v[200:201], off
	v_lshl_add_u64 v[200:201], v[210:211], 0, s[42:43]
	s_add_i32 m0, s44, 0x8000
	s_nop 0
	global_load_lds_dwordx4 v[200:201], off
	v_lshl_add_u64 v[200:201], v[212:213], 0, s[42:43]
	s_add_i32 m0, s44, 0xa000
	s_nop 0
	global_load_lds_dwordx4 v[200:201], off
	s_waitcnt vmcnt(8)
	s_waitcnt lgkmcnt(0)
	s_setprio 1
	s_barrier
	v_mfma_f32_16x16x32_bf16 v[62:65], v[90:93], v[164:167], v[62:65]
	v_mfma_f32_16x16x32_bf16 v[58:61], v[100:103], v[164:167], v[58:61]
	v_mfma_f32_16x16x32_bf16 v[46:49], v[90:93], v[172:175], v[46:49]
	v_mfma_f32_16x16x32_bf16 v[42:45], v[100:103], v[172:175], v[42:45]
	v_mfma_f32_16x16x32_bf16 v[30:33], v[90:93], v[180:183], v[30:33]
	v_mfma_f32_16x16x32_bf16 v[26:29], v[100:103], v[180:183], v[26:29]
	v_mfma_f32_16x16x32_bf16 v[14:17], v[90:93], v[188:191], v[14:17]
	v_mfma_f32_16x16x32_bf16 v[10:13], v[100:103], v[188:191], v[10:13]
	v_mfma_f32_16x16x32_bf16 v[62:65], v[94:97], v[168:171], v[62:65]
	v_mfma_f32_16x16x32_bf16 v[58:61], v[104:107], v[168:171], v[58:61]
	v_mfma_f32_16x16x32_bf16 v[46:49], v[94:97], v[176:179], v[46:49]
	v_mfma_f32_16x16x32_bf16 v[42:45], v[104:107], v[176:179], v[42:45]
	v_mfma_f32_16x16x32_bf16 v[30:33], v[94:97], v[184:187], v[30:33]
	v_mfma_f32_16x16x32_bf16 v[26:29], v[104:107], v[184:187], v[26:29]
	v_mfma_f32_16x16x32_bf16 v[14:17], v[94:97], v[192:195], v[14:17]
	v_mfma_f32_16x16x32_bf16 v[10:13], v[104:107], v[192:195], v[10:13]
	s_setprio 0
	s_setprio 1
	v_mfma_f32_16x16x32_bf16 v[54:57], v[108:111], v[164:167], v[54:57]
	v_mfma_f32_16x16x32_bf16 v[50:53], v[120:123], v[164:167], v[50:53]
	v_mfma_f32_16x16x32_bf16 v[38:41], v[108:111], v[172:175], v[38:41]
	v_mfma_f32_16x16x32_bf16 v[34:37], v[120:123], v[172:175], v[34:37]
	v_mfma_f32_16x16x32_bf16 v[22:25], v[108:111], v[180:183], v[22:25]
	v_mfma_f32_16x16x32_bf16 v[18:21], v[120:123], v[180:183], v[18:21]
	v_mfma_f32_16x16x32_bf16 v[6:9], v[108:111], v[188:191], v[6:9]
	v_mfma_f32_16x16x32_bf16 v[2:5], v[120:123], v[188:191], v[2:5]
	v_mfma_f32_16x16x32_bf16 v[54:57], v[112:115], v[168:171], v[54:57]
	v_mfma_f32_16x16x32_bf16 v[50:53], v[128:131], v[168:171], v[50:53]
	v_mfma_f32_16x16x32_bf16 v[38:41], v[112:115], v[176:179], v[38:41]
	v_mfma_f32_16x16x32_bf16 v[34:37], v[128:131], v[176:179], v[34:37]
	v_mfma_f32_16x16x32_bf16 v[22:25], v[112:115], v[184:187], v[22:25]
	v_mfma_f32_16x16x32_bf16 v[18:21], v[128:131], v[184:187], v[18:21]
	v_mfma_f32_16x16x32_bf16 v[6:9], v[112:115], v[192:195], v[6:9]
	v_mfma_f32_16x16x32_bf16 v[2:5], v[128:131], v[192:195], v[2:5]
	s_setprio 0
	s_barrier
	s_mov_b32 s100, 0
	s_add_i32 s95, s95, 2
	s_add_u32 s70, s70, 0x100
	s_addc_u32 s71, s71, 0
	s_add_u32 s69, s69, 0x100
	s_addc_u32 s94, s94, 0
	s_cmp_gt_u32 s95, 61
	s_cbranch_scc0 .LBB0_1172
	s_mov_b32 s100, 1
	s_and_b64 vcc, exec, s[10:11]
	s_cbranch_vccz .LBB0_1175
	s_barrier
